# v14 plus removal of the redundant s_waitcnt lgkmcnt(0) between each K-loop barrier release and its first MFMA
# baseline (speedup 1.0000x reference)
; #define PG8_STAGE(bufoff, gbase, voff) do { _Pragma("unroll") for (int _i = 0; _i < 2; ++_i) \
;         __builtin_amdgcn_global_load_lds((const unsigned*)((const char*)(gbase) + (voff)[_i]), (LAS unsigned*)(lds + (bufoff) + ldsw + _i * 8192), 16, 0, 0); } while (0)
; #define PG8_LDA(dst, b, h) do { _Pragma("unroll") for (int m = 0; m < 4; ++m) _Pragma("unroll") for (int k = 0; k < 2; ++k) dst[m][k] = *(const LAS bf16x8*)(lds + PG8_SA(b, h) + aoff + m * 2048 + k * 1024); } while (0)
; #define PG8_LDB(dst, b, h) do { _Pragma("unroll") for (int n = 0; n < 2; ++n) _Pragma("unroll") for (int k = 0; k < 2; ++k) dst[n][k] = *(const LAS bf16x8*)(lds + PG8_SB(b, h) + boff + n * 2048 + k * 1024); } while (0)
; #define PG8_WAIT_V(n) asm volatile("s_waitcnt vmcnt(" #n ")" ::: "memory")
; #define PG8_WAIT_L(n) asm volatile("s_waitcnt lgkmcnt(" #n ")" ::: "memory")
; #define PG8_BAR __builtin_amdgcn_s_barrier()
; #define PG8_SCHED __builtin_amdgcn_sched_barrier(0)
; template <class Epi>
; __device__ __forceinline__ void gemm_phase(LAS unsigned char* lds, const Gemm g, const Order& S, const Epi& E) {
;     ...
;             PG8_LDB(B0, 0, 0); PG8_LDB(B1, 0, 1); PG8_SCHED; PG8_LDA(At, 0, 0); PG8_STAGE(PG8_SA(1, 1), a1 + hstepA, voffA);
;             PG8_WAIT_V(8); PG8_WAIT_L(0); PG8_BAR; PG8_MMA(0, 0, At, B0); PG8_MMA(0, 1, At, B1); PG8_BAR; PG8_SCHED;
;             PG8_LDA(At, 0, 1); PG8_STAGE(PG8_SB(0, 0), b2, voffB); PG8_STAGE(PG8_SB(0, 1), b2 + hstepB, voffB); PG8_STAGE(PG8_SA(0, 0), a2, voffA);
;             PG8_WAIT_V(8); PG8_WAIT_L(0); PG8_BAR; PG8_MMA(1, 0, At, B0); PG8_MMA(1, 1, At, B1); PG8_BAR; PG8_SCHED;
.LBB0_81:
	s_add_u32 s4, s40, 0xfffc0080
	s_addc_u32 s5, s41, -1
	s_add_i32 s6, 0, 0x10000
	s_cmp_eq_u32 vcc_lo, 12
	s_cselect_b32 s71, s34, s5
	s_cselect_b32 s70, s35, s4
	v_add_u32_e32 v142, s6, v145
	s_cselect_b32 s69, s45, s89
	s_cselect_b32 s68, s47, s88
	s_add_i32 s7, 0, 0x14000
	ds_read_b128 v[138:141], v142
	ds_read_b128 v[148:151], v142 offset:1024
	ds_read_b128 v[152:155], v142 offset:2048
	ds_read_b128 v[156:159], v142 offset:3072
	v_add_u32_e32 v142, s7, v145
	ds_read_b128 v[172:175], v142
	ds_read_b128 v[176:179], v142 offset:1024
	ds_read_b128 v[180:183], v142 offset:2048
	ds_read_b128 v[184:187], v142 offset:3072
	v_lshl_add_u64 v[142:143], s[40:41], 0, v[134:135]
	s_add_i32 m0, s24, 0xc000
	ds_read_b128 v[188:191], v147
	ds_read_b128 v[192:195], v147 offset:1024
	ds_read_b128 v[214:217], v147 offset:2048
	ds_read_b128 v[218:221], v147 offset:3072
	ds_read_b128 v[222:225], v147 offset:4096
	ds_read_b128 v[226:229], v147 offset:5120
	ds_read_b128 v[230:233], v147 offset:6144
	ds_read_b128 v[234:237], v147 offset:7168
	global_load_lds_dwordx4 v[142:143], off
	v_lshl_add_u64 v[142:143], s[40:41], 0, v[136:137]
	s_add_i32 m0, s24, 0xe000
	s_nop 0
	global_load_lds_dwordx4 v[142:143], off
	s_waitcnt vmcnt(8)
	s_waitcnt lgkmcnt(0)
	s_barrier
	s_setprio 1
	v_mfma_f32_16x16x32_f16 v[124:127], v[138:141], v[188:191], v[124:127]
	v_mfma_f32_16x16x32_f16 v[120:123], v[152:155], v[188:191], v[120:123]
	v_mfma_f32_16x16x32_f16 v[108:111], v[138:141], v[214:217], v[108:111]
	v_mfma_f32_16x16x32_f16 v[104:107], v[152:155], v[214:217], v[104:107]
	v_mfma_f32_16x16x32_f16 v[92:95], v[138:141], v[222:225], v[92:95]
	v_mfma_f32_16x16x32_f16 v[88:91], v[152:155], v[222:225], v[88:91]
	v_mfma_f32_16x16x32_f16 v[76:79], v[138:141], v[230:233], v[76:79]
	v_mfma_f32_16x16x32_f16 v[72:75], v[152:155], v[230:233], v[72:75]
	v_mfma_f32_16x16x32_f16 v[124:127], v[148:151], v[192:195], v[124:127]
	v_mfma_f32_16x16x32_f16 v[120:123], v[156:159], v[192:195], v[120:123]
	v_mfma_f32_16x16x32_f16 v[108:111], v[148:151], v[218:221], v[108:111]
	v_mfma_f32_16x16x32_f16 v[104:107], v[156:159], v[218:221], v[104:107]
	v_mfma_f32_16x16x32_f16 v[92:95], v[148:151], v[226:229], v[92:95]
	v_mfma_f32_16x16x32_f16 v[88:91], v[156:159], v[226:229], v[88:91]
	v_mfma_f32_16x16x32_f16 v[76:79], v[148:151], v[234:237], v[76:79]
	v_mfma_f32_16x16x32_f16 v[72:75], v[156:159], v[234:237], v[72:75]
	v_mfma_f32_16x16x32_f16 v[116:119], v[172:175], v[188:191], v[116:119]
	v_mfma_f32_16x16x32_f16 v[112:115], v[180:183], v[188:191], v[112:115]
	v_mfma_f32_16x16x32_f16 v[100:103], v[172:175], v[214:217], v[100:103]
	v_mfma_f32_16x16x32_f16 v[96:99], v[180:183], v[214:217], v[96:99]
	v_mfma_f32_16x16x32_f16 v[84:87], v[172:175], v[222:225], v[84:87]
	v_mfma_f32_16x16x32_f16 v[80:83], v[180:183], v[222:225], v[80:83]
	v_mfma_f32_16x16x32_f16 v[68:71], v[172:175], v[230:233], v[68:71]
	v_mfma_f32_16x16x32_f16 v[64:67], v[180:183], v[230:233], v[64:67]
	v_mfma_f32_16x16x32_f16 v[116:119], v[176:179], v[192:195], v[116:119]
	v_mfma_f32_16x16x32_f16 v[112:115], v[184:187], v[192:195], v[112:115]
	v_mfma_f32_16x16x32_f16 v[100:103], v[176:179], v[218:221], v[100:103]
	v_mfma_f32_16x16x32_f16 v[96:99], v[184:187], v[218:221], v[96:99]
	v_mfma_f32_16x16x32_f16 v[84:87], v[176:179], v[226:229], v[84:87]
	v_mfma_f32_16x16x32_f16 v[80:83], v[184:187], v[226:229], v[80:83]
	v_mfma_f32_16x16x32_f16 v[68:71], v[176:179], v[234:237], v[68:71]
	v_mfma_f32_16x16x32_f16 v[64:67], v[184:187], v[234:237], v[64:67]
	s_setprio 0
	s_barrier
	s_add_i32 s4, s6, s23
	v_lshl_add_u64 v[142:143], s[68:69], 0, v[160:161]
	s_mov_b32 m0, s4
	ds_read_b128 v[188:191], v147 offset:16384
	ds_read_b128 v[192:195], v147 offset:17408
	ds_read_b128 v[214:217], v147 offset:18432
	ds_read_b128 v[218:221], v147 offset:19456
	ds_read_b128 v[222:225], v147 offset:20480
	ds_read_b128 v[226:229], v147 offset:21504
	ds_read_b128 v[230:233], v147 offset:22528
	ds_read_b128 v[234:237], v147 offset:23552
	global_load_lds_dwordx4 v[142:143], off
	s_add_i32 m0, s4, 0x2000
	s_add_u32 s4, s68, 0x40000
	v_lshl_add_u64 v[200:201], s[68:69], 0, v[128:129]
	s_addc_u32 s5, s69, 0
	s_add_i32 s6, s7, s23
	global_load_lds_dwordx4 v[200:201], off
	v_lshl_add_u64 v[238:239], s[4:5], 0, v[160:161]
	s_mov_b32 m0, s6
	v_lshl_add_u64 v[240:241], s[70:71], 0, v[130:131]
	global_load_lds_dwordx4 v[238:239], off
	v_lshl_add_u64 v[238:239], s[4:5], 0, v[128:129]
	s_add_i32 m0, s6, 0x2000
	s_nop 0
	global_load_lds_dwordx4 v[238:239], off
	v_lshl_add_u64 v[238:239], s[70:71], 0, v[132:133]
	s_mov_b32 m0, s24
	s_nop 0
	global_load_lds_dwordx4 v[238:239], off
	s_mov_b32 m0, s25
	s_nop 0
	global_load_lds_dwordx4 v[240:241], off
	s_waitcnt vmcnt(8)
	s_waitcnt lgkmcnt(0)
	s_barrier
; #define PG8_STAGE(bufoff, gbase, voff) do { _Pragma("unroll") for (int _i = 0; _i < 2; ++_i) \
;         __builtin_amdgcn_global_load_lds((const unsigned*)((const char*)(gbase) + (voff)[_i]), (LAS unsigned*)(lds + (bufoff) + ldsw + _i * 8192), 16, 0, 0); } while (0)
; #define PG8_LDA(dst, b, h) do { _Pragma("unroll") for (int m = 0; m < 4; ++m) _Pragma("unroll") for (int k = 0; k < 2; ++k) dst[m][k] = *(const LAS bf16x8*)(lds + PG8_SA(b, h) + aoff + m * 2048 + k * 1024); } while (0)
; #define PG8_LDB(dst, b, h) do { _Pragma("unroll") for (int n = 0; n < 2; ++n) _Pragma("unroll") for (int k = 0; k < 2; ++k) dst[n][k] = *(const LAS bf16x8*)(lds + PG8_SB(b, h) + boff + n * 2048 + k * 1024); } while (0)
; #define PG8_WAIT_V(n) asm volatile("s_waitcnt vmcnt(" #n ")" ::: "memory")
; #define PG8_WAIT_L(n) asm volatile("s_waitcnt lgkmcnt(" #n ")" ::: "memory")
; #define PG8_BAR __builtin_amdgcn_s_barrier()
; #define PG8_SCHED __builtin_amdgcn_sched_barrier(0)
; template <class Epi>
; __device__ __forceinline__ void gemm_phase(LAS unsigned char* lds, const Gemm g, const Order& S, const Epi& E) {
;     ...
;             PG8_WAIT_V(8); PG8_WAIT_L(0); PG8_BAR; PG8_MMA(1, 0, At, B0); PG8_MMA(1, 1, At, B1); PG8_BAR; PG8_SCHED;
;             PG8_LDB(B0, 1, 0); PG8_LDB(B1, 1, 1); PG8_SCHED; PG8_LDA(At, 1, 0); PG8_STAGE(PG8_SA(0, 1), a2 + hstepA, voffA);
;             PG8_WAIT_V(8); PG8_WAIT_L(0); PG8_BAR; PG8_MMA(0, 0, At, B0); PG8_MMA(0, 1, At, B1); PG8_BAR; PG8_SCHED;
	s_setprio 1
	v_mfma_f32_16x16x32_f16 v[60:63], v[138:141], v[188:191], v[60:63]
	v_mfma_f32_16x16x32_f16 v[56:59], v[152:155], v[188:191], v[56:59]
	v_mfma_f32_16x16x32_f16 v[44:47], v[138:141], v[214:217], v[44:47]
	v_mfma_f32_16x16x32_f16 v[40:43], v[152:155], v[214:217], v[40:43]
	v_mfma_f32_16x16x32_f16 v[28:31], v[138:141], v[222:225], v[28:31]
	v_mfma_f32_16x16x32_f16 v[24:27], v[152:155], v[222:225], v[24:27]
	v_mfma_f32_16x16x32_f16 v[12:15], v[138:141], v[230:233], v[12:15]
	v_mfma_f32_16x16x32_f16 v[8:11], v[152:155], v[230:233], v[8:11]
	v_mfma_f32_16x16x32_f16 v[60:63], v[148:151], v[192:195], v[60:63]
	v_mfma_f32_16x16x32_f16 v[56:59], v[156:159], v[192:195], v[56:59]
	v_mfma_f32_16x16x32_f16 v[44:47], v[148:151], v[218:221], v[44:47]
	v_mfma_f32_16x16x32_f16 v[40:43], v[156:159], v[218:221], v[40:43]
	v_mfma_f32_16x16x32_f16 v[28:31], v[148:151], v[226:229], v[28:31]
	v_mfma_f32_16x16x32_f16 v[24:27], v[156:159], v[226:229], v[24:27]
	v_mfma_f32_16x16x32_f16 v[12:15], v[148:151], v[234:237], v[12:15]
	v_mfma_f32_16x16x32_f16 v[8:11], v[156:159], v[234:237], v[8:11]
	v_mfma_f32_16x16x32_f16 v[52:55], v[172:175], v[188:191], v[52:55]
	v_mfma_f32_16x16x32_f16 v[48:51], v[180:183], v[188:191], v[48:51]
	v_mfma_f32_16x16x32_f16 v[36:39], v[172:175], v[214:217], v[36:39]
	v_mfma_f32_16x16x32_f16 v[32:35], v[180:183], v[214:217], v[32:35]
	v_mfma_f32_16x16x32_f16 v[20:23], v[172:175], v[222:225], v[20:23]
	v_mfma_f32_16x16x32_f16 v[16:19], v[180:183], v[222:225], v[16:19]
	v_mfma_f32_16x16x32_f16 v[4:7], v[172:175], v[230:233], v[4:7]
	v_mfma_f32_16x16x32_f16 v[0:3], v[180:183], v[230:233], v[0:3]
	v_mfma_f32_16x16x32_f16 v[52:55], v[176:179], v[192:195], v[52:55]
	v_mfma_f32_16x16x32_f16 v[48:51], v[184:187], v[192:195], v[48:51]
	v_mfma_f32_16x16x32_f16 v[36:39], v[176:179], v[218:221], v[36:39]
	v_mfma_f32_16x16x32_f16 v[32:35], v[184:187], v[218:221], v[32:35]
	v_mfma_f32_16x16x32_f16 v[20:23], v[176:179], v[226:229], v[20:23]
	v_mfma_f32_16x16x32_f16 v[16:19], v[184:187], v[226:229], v[16:19]
	v_mfma_f32_16x16x32_f16 v[4:7], v[176:179], v[234:237], v[4:7]
	v_mfma_f32_16x16x32_f16 v[0:3], v[184:187], v[234:237], v[0:3]
	s_setprio 0
	s_barrier
	s_add_i32 s6, 0, 0x18000
	s_add_i32 s7, 0, 0x1c000
	v_add_u32_e32 v156, s6, v145
	v_add_u32_e32 v171, s7, v145
	ds_read_b128 v[138:141], v156
	ds_read_b128 v[148:151], v156 offset:1024
	ds_read_b128 v[152:155], v156 offset:2048
	ds_read_b128 v[156:159], v156 offset:3072
	ds_read_b128 v[172:175], v171
	ds_read_b128 v[176:179], v171 offset:1024
	ds_read_b128 v[180:183], v171 offset:2048
	ds_read_b128 v[184:187], v171 offset:3072
	s_add_u32 s4, s70, 0x40000
	s_addc_u32 s5, s71, 0
	s_mov_b32 m0, s26
	v_lshl_add_u64 v[242:243], s[4:5], 0, v[132:133]
	ds_read_b128 v[188:191], v147 offset:32768
	ds_read_b128 v[192:195], v147 offset:33792
	ds_read_b128 v[214:217], v147 offset:34816
	ds_read_b128 v[218:221], v147 offset:35840
	ds_read_b128 v[222:225], v147 offset:36864
	ds_read_b128 v[226:229], v147 offset:37888
	ds_read_b128 v[230:233], v147 offset:38912
	ds_read_b128 v[234:237], v147 offset:39936
	global_load_lds_dwordx4 v[242:243], off
	v_lshl_add_u64 v[242:243], s[4:5], 0, v[130:131]
	s_mov_b32 m0, s27
	s_nop 0
	global_load_lds_dwordx4 v[242:243], off
	s_waitcnt vmcnt(8)
	s_waitcnt lgkmcnt(0)
	s_barrier
	s_setprio 1
	v_mfma_f32_16x16x32_f16 v[124:127], v[138:141], v[188:191], v[124:127]
	v_mfma_f32_16x16x32_f16 v[120:123], v[152:155], v[188:191], v[120:123]
	v_mfma_f32_16x16x32_f16 v[108:111], v[138:141], v[214:217], v[108:111]
	v_mfma_f32_16x16x32_f16 v[104:107], v[152:155], v[214:217], v[104:107]
	v_mfma_f32_16x16x32_f16 v[92:95], v[138:141], v[222:225], v[92:95]
	v_mfma_f32_16x16x32_f16 v[88:91], v[152:155], v[222:225], v[88:91]
	v_mfma_f32_16x16x32_f16 v[76:79], v[138:141], v[230:233], v[76:79]
	v_mfma_f32_16x16x32_f16 v[72:75], v[152:155], v[230:233], v[72:75]
	v_mfma_f32_16x16x32_f16 v[124:127], v[148:151], v[192:195], v[124:127]
	v_mfma_f32_16x16x32_f16 v[120:123], v[156:159], v[192:195], v[120:123]
	v_mfma_f32_16x16x32_f16 v[108:111], v[148:151], v[218:221], v[108:111]
	v_mfma_f32_16x16x32_f16 v[104:107], v[156:159], v[218:221], v[104:107]
	v_mfma_f32_16x16x32_f16 v[92:95], v[148:151], v[226:229], v[92:95]
	v_mfma_f32_16x16x32_f16 v[88:91], v[156:159], v[226:229], v[88:91]
	v_mfma_f32_16x16x32_f16 v[76:79], v[148:151], v[234:237], v[76:79]
	v_mfma_f32_16x16x32_f16 v[72:75], v[156:159], v[234:237], v[72:75]
	v_mfma_f32_16x16x32_f16 v[116:119], v[172:175], v[188:191], v[116:119]
	v_mfma_f32_16x16x32_f16 v[112:115], v[180:183], v[188:191], v[112:115]
	v_mfma_f32_16x16x32_f16 v[100:103], v[172:175], v[214:217], v[100:103]
	v_mfma_f32_16x16x32_f16 v[96:99], v[180:183], v[214:217], v[96:99]
	v_mfma_f32_16x16x32_f16 v[84:87], v[172:175], v[222:225], v[84:87]
	v_mfma_f32_16x16x32_f16 v[80:83], v[180:183], v[222:225], v[80:83]
	v_mfma_f32_16x16x32_f16 v[68:71], v[172:175], v[230:233], v[68:71]
	v_mfma_f32_16x16x32_f16 v[64:67], v[180:183], v[230:233], v[64:67]
	v_mfma_f32_16x16x32_f16 v[116:119], v[176:179], v[192:195], v[116:119]
	v_mfma_f32_16x16x32_f16 v[112:115], v[184:187], v[192:195], v[112:115]
	v_mfma_f32_16x16x32_f16 v[100:103], v[176:179], v[218:221], v[100:103]
	v_mfma_f32_16x16x32_f16 v[96:99], v[184:187], v[218:221], v[96:99]
	v_mfma_f32_16x16x32_f16 v[84:87], v[176:179], v[226:229], v[84:87]
	v_mfma_f32_16x16x32_f16 v[80:83], v[184:187], v[226:229], v[80:83]
	v_mfma_f32_16x16x32_f16 v[68:71], v[176:179], v[234:237], v[68:71]
	v_mfma_f32_16x16x32_f16 v[64:67], v[184:187], v[234:237], v[64:67]
	s_setprio 0
	s_barrier
; #define PG8_STAGE(bufoff, gbase, voff) do { _Pragma("unroll") for (int _i = 0; _i < 2; ++_i) \
;         __builtin_amdgcn_global_load_lds((const unsigned*)((const char*)(gbase) + (voff)[_i]), (LAS unsigned*)(lds + (bufoff) + ldsw + _i * 8192), 16, 0, 0); } while (0)
; #define PG8_LDA(dst, b, h) do { _Pragma("unroll") for (int m = 0; m < 4; ++m) _Pragma("unroll") for (int k = 0; k < 2; ++k) dst[m][k] = *(const LAS bf16x8*)(lds + PG8_SA(b, h) + aoff + m * 2048 + k * 1024); } while (0)
; #define PG8_WAIT_V(n) asm volatile("s_waitcnt vmcnt(" #n ")" ::: "memory")
; #define PG8_WAIT_L(n) asm volatile("s_waitcnt lgkmcnt(" #n ")" ::: "memory")
; #define PG8_BAR __builtin_amdgcn_s_barrier()
; #define PG8_SCHED __builtin_amdgcn_sched_barrier(0)
; template <class Epi>
; __device__ __forceinline__ void gemm_phase(LAS unsigned char* lds, const Gemm g, const Order& S, const Epi& E) {
;     ...
;             PG8_LDA(At, 1, 1); PG8_STAGE(PG8_SB(1, 0), b3, voffB); PG8_STAGE(PG8_SB(1, 1), b3 + hstepB, voffB); PG8_STAGE(PG8_SA(1, 0), a3, voffA);
;             PG8_WAIT_V(8); PG8_WAIT_L(0); PG8_BAR; PG8_MMA(1, 0, At, B0); PG8_MMA(1, 1, At, B1); PG8_BAR; PG8_SCHED;
;         }
;         if constexpr (ALIGN_EPI) { if (wr == 0) PG8_BAR; }
;         if constexpr (!Epi::AFTER_DRAIN) E(acc, cur, wr, wc, fr, fq);
;         if (!has_next) break;
	s_add_i32 s4, s6, s23
	v_lshl_add_u64 v[142:143], v[142:143], 0, s[62:63]
	s_mov_b32 m0, s4
	ds_read_b128 v[188:191], v147 offset:49152
	ds_read_b128 v[192:195], v147 offset:50176
	ds_read_b128 v[214:217], v147 offset:51200
	ds_read_b128 v[218:221], v147 offset:52224
	ds_read_b128 v[222:225], v147 offset:53248
	ds_read_b128 v[226:229], v147 offset:54272
	ds_read_b128 v[230:233], v147 offset:55296
	ds_read_b128 v[234:237], v147 offset:56320
	global_load_lds_dwordx4 v[142:143], off
	s_add_i32 m0, s4, 0x2000
	s_add_u32 s4, s68, 0x40080
	v_lshl_add_u64 v[142:143], v[200:201], 0, s[62:63]
	s_addc_u32 s5, s69, 0
	s_add_i32 s6, s7, s23
	global_load_lds_dwordx4 v[142:143], off
	v_lshl_add_u64 v[142:143], s[4:5], 0, v[160:161]
	s_mov_b32 m0, s6
	s_nop 0
	global_load_lds_dwordx4 v[142:143], off
	v_lshl_add_u64 v[142:143], s[4:5], 0, v[128:129]
	s_add_i32 m0, s6, 0x2000
	s_nop 0
	global_load_lds_dwordx4 v[142:143], off
	v_lshl_add_u64 v[142:143], v[238:239], 0, s[62:63]
	s_mov_b32 m0, s28
	s_nop 0
	global_load_lds_dwordx4 v[142:143], off
	v_lshl_add_u64 v[142:143], v[240:241], 0, s[62:63]
	s_mov_b32 m0, s29
	s_nop 0
	global_load_lds_dwordx4 v[142:143], off
	s_waitcnt vmcnt(8)
	s_waitcnt lgkmcnt(0)
	s_barrier
	s_setprio 1
	v_mfma_f32_16x16x32_f16 v[60:63], v[138:141], v[188:191], v[60:63]
	v_mfma_f32_16x16x32_f16 v[56:59], v[152:155], v[188:191], v[56:59]
	v_mfma_f32_16x16x32_f16 v[44:47], v[138:141], v[214:217], v[44:47]
	v_mfma_f32_16x16x32_f16 v[40:43], v[152:155], v[214:217], v[40:43]
	v_mfma_f32_16x16x32_f16 v[28:31], v[138:141], v[222:225], v[28:31]
	v_mfma_f32_16x16x32_f16 v[24:27], v[152:155], v[222:225], v[24:27]
	v_mfma_f32_16x16x32_f16 v[12:15], v[138:141], v[230:233], v[12:15]
	v_mfma_f32_16x16x32_f16 v[8:11], v[152:155], v[230:233], v[8:11]
	v_mfma_f32_16x16x32_f16 v[60:63], v[148:151], v[192:195], v[60:63]
	v_mfma_f32_16x16x32_f16 v[56:59], v[156:159], v[192:195], v[56:59]
	v_mfma_f32_16x16x32_f16 v[44:47], v[148:151], v[218:221], v[44:47]
	v_mfma_f32_16x16x32_f16 v[40:43], v[156:159], v[218:221], v[40:43]
	v_mfma_f32_16x16x32_f16 v[28:31], v[148:151], v[226:229], v[28:31]
	v_mfma_f32_16x16x32_f16 v[24:27], v[156:159], v[226:229], v[24:27]
	v_mfma_f32_16x16x32_f16 v[12:15], v[148:151], v[234:237], v[12:15]
	v_mfma_f32_16x16x32_f16 v[8:11], v[156:159], v[234:237], v[8:11]
	v_mfma_f32_16x16x32_f16 v[52:55], v[172:175], v[188:191], v[52:55]
	v_mfma_f32_16x16x32_f16 v[48:51], v[180:183], v[188:191], v[48:51]
	v_mfma_f32_16x16x32_f16 v[36:39], v[172:175], v[214:217], v[36:39]
	v_mfma_f32_16x16x32_f16 v[32:35], v[180:183], v[214:217], v[32:35]
	v_mfma_f32_16x16x32_f16 v[20:23], v[172:175], v[222:225], v[20:23]
	v_mfma_f32_16x16x32_f16 v[16:19], v[180:183], v[222:225], v[16:19]
	v_mfma_f32_16x16x32_f16 v[4:7], v[172:175], v[230:233], v[4:7]
	v_mfma_f32_16x16x32_f16 v[0:3], v[180:183], v[230:233], v[0:3]
	v_mfma_f32_16x16x32_f16 v[52:55], v[176:179], v[192:195], v[52:55]
	v_mfma_f32_16x16x32_f16 v[48:51], v[184:187], v[192:195], v[48:51]
	v_mfma_f32_16x16x32_f16 v[36:39], v[176:179], v[218:221], v[36:39]
	v_mfma_f32_16x16x32_f16 v[32:35], v[184:187], v[218:221], v[32:35]
	v_mfma_f32_16x16x32_f16 v[20:23], v[176:179], v[226:229], v[20:23]
	v_mfma_f32_16x16x32_f16 v[16:19], v[184:187], v[226:229], v[16:19]
	v_mfma_f32_16x16x32_f16 v[4:7], v[176:179], v[234:237], v[4:7]
	v_mfma_f32_16x16x32_f16 v[0:3], v[184:187], v[234:237], v[0:3]
	s_setprio 0
	s_barrier
	s_add_i32 vcc_lo, vcc_lo, 2
	s_add_u32 s40, s40, 0x100
	s_addc_u32 s41, s41, 0
	s_add_u32 s88, s88, 0x100
	s_addc_u32 s89, s89, 0
	s_cmp_gt_u32 vcc_lo, 13
	s_cbranch_scc0 .LBB0_81
	s_and_b64 vcc, exec, s[42:43]
	s_cbranch_vccz .LBB0_84
	s_barrier

; #define PG8_STAGE(bufoff, gbase, voff) do { _Pragma("unroll") for (int _i = 0; _i < 2; ++_i) \
;         __builtin_amdgcn_global_load_lds((const unsigned*)((const char*)(gbase) + (voff)[_i]), (LAS unsigned*)(lds + (bufoff) + ldsw + _i * 8192), 16, 0, 0); } while (0)
; #define PG8_LDA(dst, b, h) do { _Pragma("unroll") for (int m = 0; m < 4; ++m) _Pragma("unroll") for (int k = 0; k < 2; ++k) dst[m][k] = *(const LAS bf16x8*)(lds + PG8_SA(b, h) + aoff + m * 2048 + k * 1024); } while (0)
; #define PG8_LDB(dst, b, h) do { _Pragma("unroll") for (int n = 0; n < 2; ++n) _Pragma("unroll") for (int k = 0; k < 2; ++k) dst[n][k] = *(const LAS bf16x8*)(lds + PG8_SB(b, h) + boff + n * 2048 + k * 1024); } while (0)
; #define PG8_WAIT_V(n) asm volatile("s_waitcnt vmcnt(" #n ")" ::: "memory")
; #define PG8_WAIT_L(n) asm volatile("s_waitcnt lgkmcnt(" #n ")" ::: "memory")
; #define PG8_BAR __builtin_amdgcn_s_barrier()
; #define PG8_SCHED __builtin_amdgcn_sched_barrier(0)
; template <class Epi>
; __device__ __forceinline__ void gemm_phase(LAS unsigned char* lds, const Gemm g, const Order& S, const Epi& E) {
;     ...
;         const bool has_next = S.next(ui + 1, nxt);
;         const char* nA = has_next ? (const char*)(g.A + (size_t)nxt.pm * BM * g.lda + (size_t)nxt.z * g.za) : cA;
;         const char* nB = has_next ? (const char*)(g.Bt + (size_t)nxt.pn * BM * g.ldb + (size_t)nxt.z * g.zb) : cB;
;         for (int t = 0; t < nt; t += 2) {
;             const bool last = (t == nt - 2);
;             const char* a1 = cA + (size_t)(t + 1) * kstep;
;             const char* a2 = last ? nA : cA + (size_t)(t + 2) * kstep; const char* b2 = last ? nB : cB + (size_t)(t + 2) * kstep;
;             const char* a3 = a2 + kstep; const char* b3 = b2 + kstep;
;             PG8_LDB(B0, 0, 0); PG8_LDB(B1, 0, 1); PG8_SCHED; PG8_LDA(At, 0, 0); PG8_STAGE(PG8_SA(1, 1), a1 + hstepA, voffA);
;             PG8_WAIT_V(8); PG8_WAIT_L(0); PG8_BAR; PG8_MMA(0, 0, At, B0); PG8_MMA(0, 1, At, B1); PG8_BAR; PG8_SCHED;
;             PG8_LDA(At, 0, 1); PG8_STAGE(PG8_SB(0, 0), b2, voffB); PG8_STAGE(PG8_SB(0, 1), b2 + hstepB, voffB); PG8_STAGE(PG8_SA(0, 0), a2, voffA);
;             PG8_WAIT_V(8); PG8_WAIT_L(0); PG8_BAR; PG8_MMA(1, 0, At, B0); PG8_MMA(1, 1, At, B1); PG8_BAR; PG8_SCHED;
.LBB0_172:
	s_add_i32 s36, s35, 2
	s_add_u32 s4, s70, vcc_lo
	s_addc_u32 s5, s71, vcc_hi
	s_add_u32 s37, s68, vcc_lo
	s_addc_u32 s6, s69, vcc_hi
	s_add_i32 s7, 0, 0x10000
	s_cmp_eq_u32 s49, s35
	s_cselect_b32 s65, s45, s5
	s_cselect_b32 s64, s44, s4
	v_add_u32_e32 v158, s7, v143
	s_cselect_b32 s5, s89, s6
	s_cselect_b32 s4, s88, s37
	s_add_i32 s6, 0, 0x14000
	ds_read_b128 v[146:149], v158
	ds_read_b128 v[150:153], v158 offset:1024
	ds_read_b128 v[154:157], v158 offset:2048
	ds_read_b128 v[172:175], v158 offset:3072
	v_add_u32_e32 v158, s6, v143
	ds_read_b128 v[176:179], v158
	ds_read_b128 v[180:183], v158 offset:1024
	ds_read_b128 v[184:187], v158 offset:2048
	ds_read_b128 v[188:191], v158 offset:3072
	v_lshl_add_u64 v[158:159], s[70:71], 0, v[140:141]
	s_add_i32 m0, s67, 0xc000
	ds_read_b128 v[192:195], v144
	ds_read_b128 v[214:217], v144 offset:1024
	ds_read_b128 v[218:221], v144 offset:2048
	ds_read_b128 v[222:225], v144 offset:3072
	ds_read_b128 v[226:229], v144 offset:4096
	ds_read_b128 v[230:233], v144 offset:5120
	ds_read_b128 v[234:237], v144 offset:6144
	ds_read_b128 v[238:241], v144 offset:7168
	global_load_lds_dwordx4 v[158:159], off
	v_lshl_add_u64 v[158:159], s[70:71], 0, v[138:139]
	s_add_i32 m0, s67, 0xe000
	s_nop 0
	global_load_lds_dwordx4 v[158:159], off
	s_waitcnt vmcnt(8)
	s_waitcnt lgkmcnt(0)
	s_barrier
	s_setprio 1
	v_mfma_f32_16x16x32_bf16 v[28:31], v[146:149], v[192:195], v[28:31]
	v_mfma_f32_16x16x32_bf16 v[24:27], v[154:157], v[192:195], v[24:27]
	v_mfma_f32_16x16x32_bf16 v[20:23], v[146:149], v[218:221], v[20:23]
	v_mfma_f32_16x16x32_bf16 v[16:19], v[154:157], v[218:221], v[16:19]
	v_mfma_f32_16x16x32_bf16 v[76:79], v[146:149], v[226:229], v[76:79]
	v_mfma_f32_16x16x32_bf16 v[72:75], v[154:157], v[226:229], v[72:75]
	v_mfma_f32_16x16x32_bf16 v[92:95], v[146:149], v[234:237], v[92:95]
	v_mfma_f32_16x16x32_bf16 v[88:91], v[154:157], v[234:237], v[88:91]
	v_mfma_f32_16x16x32_bf16 v[28:31], v[150:153], v[214:217], v[28:31]
	v_mfma_f32_16x16x32_bf16 v[24:27], v[172:175], v[214:217], v[24:27]
	v_mfma_f32_16x16x32_bf16 v[20:23], v[150:153], v[222:225], v[20:23]
	v_mfma_f32_16x16x32_bf16 v[16:19], v[172:175], v[222:225], v[16:19]
	v_mfma_f32_16x16x32_bf16 v[76:79], v[150:153], v[230:233], v[76:79]
	v_mfma_f32_16x16x32_bf16 v[72:75], v[172:175], v[230:233], v[72:75]
	v_mfma_f32_16x16x32_bf16 v[92:95], v[150:153], v[238:241], v[92:95]
	v_mfma_f32_16x16x32_bf16 v[88:91], v[172:175], v[238:241], v[88:91]
	v_mfma_f32_16x16x32_bf16 v[12:15], v[176:179], v[192:195], v[12:15]
	v_mfma_f32_16x16x32_bf16 v[8:11], v[184:187], v[192:195], v[8:11]
	v_mfma_f32_16x16x32_bf16 v[4:7], v[176:179], v[218:221], v[4:7]
	v_mfma_f32_16x16x32_bf16 v[0:3], v[184:187], v[218:221], v[0:3]
	v_mfma_f32_16x16x32_bf16 v[68:71], v[176:179], v[226:229], v[68:71]
	v_mfma_f32_16x16x32_bf16 v[64:67], v[184:187], v[226:229], v[64:67]
	v_mfma_f32_16x16x32_bf16 v[84:87], v[176:179], v[234:237], v[84:87]
	v_mfma_f32_16x16x32_bf16 v[80:83], v[184:187], v[234:237], v[80:83]
	v_mfma_f32_16x16x32_bf16 v[12:15], v[180:183], v[214:217], v[12:15]
	v_mfma_f32_16x16x32_bf16 v[8:11], v[188:191], v[214:217], v[8:11]
	v_mfma_f32_16x16x32_bf16 v[4:7], v[180:183], v[222:225], v[4:7]
	v_mfma_f32_16x16x32_bf16 v[0:3], v[188:191], v[222:225], v[0:3]
	v_mfma_f32_16x16x32_bf16 v[68:71], v[180:183], v[230:233], v[68:71]
	v_mfma_f32_16x16x32_bf16 v[64:67], v[188:191], v[230:233], v[64:67]
	v_mfma_f32_16x16x32_bf16 v[84:87], v[180:183], v[238:241], v[84:87]
	v_mfma_f32_16x16x32_bf16 v[80:83], v[188:191], v[238:241], v[80:83]
	s_setprio 0
	s_barrier
	s_add_i32 s7, s7, s29
	v_lshl_add_u64 v[158:159], s[4:5], 0, v[160:161]
	s_mov_b32 m0, s7
	ds_read_b128 v[192:195], v144 offset:16384
	ds_read_b128 v[214:217], v144 offset:17408
	ds_read_b128 v[218:221], v144 offset:18432
	ds_read_b128 v[222:225], v144 offset:19456
	ds_read_b128 v[226:229], v144 offset:20480
	ds_read_b128 v[230:233], v144 offset:21504
	ds_read_b128 v[234:237], v144 offset:22528
	ds_read_b128 v[238:241], v144 offset:23552
	global_load_lds_dwordx4 v[158:159], off
	s_add_i32 m0, s7, 0x2000
	v_lshl_add_u64 v[242:243], s[4:5], 0, v[128:129]
	s_add_u32 s4, s4, s28
	s_addc_u32 s5, s5, 0
	s_add_i32 s6, s6, s29
	global_load_lds_dwordx4 v[242:243], off
	v_lshl_add_u64 v[244:245], s[4:5], 0, v[160:161]
	s_mov_b32 m0, s6
	v_lshl_add_u64 v[246:247], s[4:5], 0, v[128:129]
	global_load_lds_dwordx4 v[244:245], off
	s_add_i32 m0, s6, 0x2000
	v_lshl_add_u64 v[248:249], s[64:65], 0, v[132:133]
	global_load_lds_dwordx4 v[246:247], off
	s_mov_b32 m0, s67
	v_lshl_add_u64 v[250:251], s[64:65], 0, v[130:131]
	global_load_lds_dwordx4 v[248:249], off
	s_mov_b32 m0, s82
	s_nop 0
	global_load_lds_dwordx4 v[250:251], off
	s_waitcnt vmcnt(8)
	s_waitcnt lgkmcnt(0)
	s_barrier
; #define PG8_STAGE(bufoff, gbase, voff) do { _Pragma("unroll") for (int _i = 0; _i < 2; ++_i) \
;         __builtin_amdgcn_global_load_lds((const unsigned*)((const char*)(gbase) + (voff)[_i]), (LAS unsigned*)(lds + (bufoff) + ldsw + _i * 8192), 16, 0, 0); } while (0)
; #define PG8_LDA(dst, b, h) do { _Pragma("unroll") for (int m = 0; m < 4; ++m) _Pragma("unroll") for (int k = 0; k < 2; ++k) dst[m][k] = *(const LAS bf16x8*)(lds + PG8_SA(b, h) + aoff + m * 2048 + k * 1024); } while (0)
; #define PG8_LDB(dst, b, h) do { _Pragma("unroll") for (int n = 0; n < 2; ++n) _Pragma("unroll") for (int k = 0; k < 2; ++k) dst[n][k] = *(const LAS bf16x8*)(lds + PG8_SB(b, h) + boff + n * 2048 + k * 1024); } while (0)
; #define PG8_WAIT_V(n) asm volatile("s_waitcnt vmcnt(" #n ")" ::: "memory")
; #define PG8_WAIT_L(n) asm volatile("s_waitcnt lgkmcnt(" #n ")" ::: "memory")
; #define PG8_BAR __builtin_amdgcn_s_barrier()
; #define PG8_SCHED __builtin_amdgcn_sched_barrier(0)
; template <class Epi>
; __device__ __forceinline__ void gemm_phase(LAS unsigned char* lds, const Gemm g, const Order& S, const Epi& E) {
;     ...
;             PG8_WAIT_V(8); PG8_WAIT_L(0); PG8_BAR; PG8_MMA(1, 0, At, B0); PG8_MMA(1, 1, At, B1); PG8_BAR; PG8_SCHED;
;             PG8_LDB(B0, 1, 0); PG8_LDB(B1, 1, 1); PG8_SCHED; PG8_LDA(At, 1, 0); PG8_STAGE(PG8_SA(0, 1), a2 + hstepA, voffA);
;             PG8_WAIT_V(8); PG8_WAIT_L(0); PG8_BAR; PG8_MMA(0, 0, At, B0); PG8_MMA(0, 1, At, B1); PG8_BAR; PG8_SCHED;
	s_setprio 1
	v_mfma_f32_16x16x32_bf16 v[124:127], v[146:149], v[192:195], v[124:127]
	v_mfma_f32_16x16x32_bf16 v[120:123], v[154:157], v[192:195], v[120:123]
	v_mfma_f32_16x16x32_bf16 v[116:119], v[146:149], v[218:221], v[116:119]
	v_mfma_f32_16x16x32_bf16 v[112:115], v[154:157], v[218:221], v[112:115]
	v_mfma_f32_16x16x32_bf16 v[60:63], v[146:149], v[226:229], v[60:63]
	v_mfma_f32_16x16x32_bf16 v[56:59], v[154:157], v[226:229], v[56:59]
	v_mfma_f32_16x16x32_bf16 v[52:55], v[146:149], v[234:237], v[52:55]
	v_mfma_f32_16x16x32_bf16 v[48:51], v[154:157], v[234:237], v[48:51]
	v_mfma_f32_16x16x32_bf16 v[124:127], v[150:153], v[214:217], v[124:127]
	v_mfma_f32_16x16x32_bf16 v[120:123], v[172:175], v[214:217], v[120:123]
	v_mfma_f32_16x16x32_bf16 v[116:119], v[150:153], v[222:225], v[116:119]
	v_mfma_f32_16x16x32_bf16 v[112:115], v[172:175], v[222:225], v[112:115]
	v_mfma_f32_16x16x32_bf16 v[60:63], v[150:153], v[230:233], v[60:63]
	v_mfma_f32_16x16x32_bf16 v[56:59], v[172:175], v[230:233], v[56:59]
	v_mfma_f32_16x16x32_bf16 v[52:55], v[150:153], v[238:241], v[52:55]
	v_mfma_f32_16x16x32_bf16 v[48:51], v[172:175], v[238:241], v[48:51]
	v_mfma_f32_16x16x32_bf16 v[108:111], v[176:179], v[192:195], v[108:111]
	v_mfma_f32_16x16x32_bf16 v[104:107], v[184:187], v[192:195], v[104:107]
	v_mfma_f32_16x16x32_bf16 v[100:103], v[176:179], v[218:221], v[100:103]
	v_mfma_f32_16x16x32_bf16 v[96:99], v[184:187], v[218:221], v[96:99]
	v_mfma_f32_16x16x32_bf16 v[44:47], v[176:179], v[226:229], v[44:47]
	v_mfma_f32_16x16x32_bf16 v[40:43], v[184:187], v[226:229], v[40:43]
	v_mfma_f32_16x16x32_bf16 v[36:39], v[176:179], v[234:237], v[36:39]
	v_mfma_f32_16x16x32_bf16 v[32:35], v[184:187], v[234:237], v[32:35]
	v_mfma_f32_16x16x32_bf16 v[108:111], v[180:183], v[214:217], v[108:111]
	v_mfma_f32_16x16x32_bf16 v[104:107], v[188:191], v[214:217], v[104:107]
	v_mfma_f32_16x16x32_bf16 v[100:103], v[180:183], v[222:225], v[100:103]
	v_mfma_f32_16x16x32_bf16 v[96:99], v[188:191], v[222:225], v[96:99]
	v_mfma_f32_16x16x32_bf16 v[44:47], v[180:183], v[230:233], v[44:47]
	v_mfma_f32_16x16x32_bf16 v[40:43], v[188:191], v[230:233], v[40:43]
	v_mfma_f32_16x16x32_bf16 v[36:39], v[180:183], v[238:241], v[36:39]
	v_mfma_f32_16x16x32_bf16 v[32:35], v[188:191], v[238:241], v[32:35]
	s_setprio 0
	s_barrier
	s_add_i32 s6, 0, 0x18000
	s_add_i32 s7, 0, 0x1c000
	v_add_u32_e32 v172, s6, v143
	v_add_u32_e32 v188, s7, v143
	ds_read_b128 v[146:149], v172
	ds_read_b128 v[150:153], v172 offset:1024
	ds_read_b128 v[154:157], v172 offset:2048
	ds_read_b128 v[172:175], v172 offset:3072
	ds_read_b128 v[176:179], v188
	ds_read_b128 v[180:183], v188 offset:1024
	ds_read_b128 v[184:187], v188 offset:2048
	ds_read_b128 v[188:191], v188 offset:3072
	s_add_u32 s4, s64, s28
	s_addc_u32 s5, s65, 0
	s_mov_b32 m0, s46
	v_lshl_add_u64 v[200:201], s[4:5], 0, v[132:133]
	ds_read_b128 v[192:195], v144 offset:32768
	ds_read_b128 v[214:217], v144 offset:33792
	ds_read_b128 v[218:221], v144 offset:34816
	ds_read_b128 v[222:225], v144 offset:35840
	ds_read_b128 v[226:229], v144 offset:36864
	ds_read_b128 v[230:233], v144 offset:37888
	ds_read_b128 v[234:237], v144 offset:38912
	ds_read_b128 v[238:241], v144 offset:39936
	global_load_lds_dwordx4 v[200:201], off
	v_lshl_add_u64 v[200:201], s[4:5], 0, v[130:131]
	s_mov_b32 m0, s47
	s_nop 0
	global_load_lds_dwordx4 v[200:201], off
	s_waitcnt vmcnt(8)
	s_waitcnt lgkmcnt(0)
	s_barrier
	s_setprio 1
	v_mfma_f32_16x16x32_bf16 v[28:31], v[146:149], v[192:195], v[28:31]
	v_mfma_f32_16x16x32_bf16 v[24:27], v[154:157], v[192:195], v[24:27]
	v_mfma_f32_16x16x32_bf16 v[20:23], v[146:149], v[218:221], v[20:23]
	v_mfma_f32_16x16x32_bf16 v[16:19], v[154:157], v[218:221], v[16:19]
	v_mfma_f32_16x16x32_bf16 v[76:79], v[146:149], v[226:229], v[76:79]
	v_mfma_f32_16x16x32_bf16 v[72:75], v[154:157], v[226:229], v[72:75]
	v_mfma_f32_16x16x32_bf16 v[92:95], v[146:149], v[234:237], v[92:95]
	v_mfma_f32_16x16x32_bf16 v[88:91], v[154:157], v[234:237], v[88:91]
	v_mfma_f32_16x16x32_bf16 v[28:31], v[150:153], v[214:217], v[28:31]
	v_mfma_f32_16x16x32_bf16 v[24:27], v[172:175], v[214:217], v[24:27]
	v_mfma_f32_16x16x32_bf16 v[20:23], v[150:153], v[222:225], v[20:23]
	v_mfma_f32_16x16x32_bf16 v[16:19], v[172:175], v[222:225], v[16:19]
	v_mfma_f32_16x16x32_bf16 v[76:79], v[150:153], v[230:233], v[76:79]
	v_mfma_f32_16x16x32_bf16 v[72:75], v[172:175], v[230:233], v[72:75]
	v_mfma_f32_16x16x32_bf16 v[92:95], v[150:153], v[238:241], v[92:95]
	v_mfma_f32_16x16x32_bf16 v[88:91], v[172:175], v[238:241], v[88:91]
	v_mfma_f32_16x16x32_bf16 v[12:15], v[176:179], v[192:195], v[12:15]
	v_mfma_f32_16x16x32_bf16 v[8:11], v[184:187], v[192:195], v[8:11]
	v_mfma_f32_16x16x32_bf16 v[4:7], v[176:179], v[218:221], v[4:7]
	v_mfma_f32_16x16x32_bf16 v[0:3], v[184:187], v[218:221], v[0:3]
	v_mfma_f32_16x16x32_bf16 v[68:71], v[176:179], v[226:229], v[68:71]
	v_mfma_f32_16x16x32_bf16 v[64:67], v[184:187], v[226:229], v[64:67]
	v_mfma_f32_16x16x32_bf16 v[84:87], v[176:179], v[234:237], v[84:87]
	v_mfma_f32_16x16x32_bf16 v[80:83], v[184:187], v[234:237], v[80:83]
	v_mfma_f32_16x16x32_bf16 v[12:15], v[180:183], v[214:217], v[12:15]
	v_mfma_f32_16x16x32_bf16 v[8:11], v[188:191], v[214:217], v[8:11]
	v_mfma_f32_16x16x32_bf16 v[4:7], v[180:183], v[222:225], v[4:7]
	v_mfma_f32_16x16x32_bf16 v[0:3], v[188:191], v[222:225], v[0:3]
	v_mfma_f32_16x16x32_bf16 v[68:71], v[180:183], v[230:233], v[68:71]
	v_mfma_f32_16x16x32_bf16 v[64:67], v[188:191], v[230:233], v[64:67]
	v_mfma_f32_16x16x32_bf16 v[84:87], v[180:183], v[238:241], v[84:87]
	v_mfma_f32_16x16x32_bf16 v[80:83], v[188:191], v[238:241], v[80:83]
	s_setprio 0
	s_barrier
; #define PG8_STAGE(bufoff, gbase, voff) do { _Pragma("unroll") for (int _i = 0; _i < 2; ++_i) \
;         __builtin_amdgcn_global_load_lds((const unsigned*)((const char*)(gbase) + (voff)[_i]), (LAS unsigned*)(lds + (bufoff) + ldsw + _i * 8192), 16, 0, 0); } while (0)
; #define PG8_LDA(dst, b, h) do { _Pragma("unroll") for (int m = 0; m < 4; ++m) _Pragma("unroll") for (int k = 0; k < 2; ++k) dst[m][k] = *(const LAS bf16x8*)(lds + PG8_SA(b, h) + aoff + m * 2048 + k * 1024); } while (0)
; #define PG8_WAIT_V(n) asm volatile("s_waitcnt vmcnt(" #n ")" ::: "memory")
; #define PG8_WAIT_L(n) asm volatile("s_waitcnt lgkmcnt(" #n ")" ::: "memory")
; #define PG8_BAR __builtin_amdgcn_s_barrier()
; #define PG8_SCHED __builtin_amdgcn_sched_barrier(0)
; template <class Epi>
; __device__ __forceinline__ void gemm_phase(LAS unsigned char* lds, const Gemm g, const Order& S, const Epi& E) {
;     ...
;             PG8_LDA(At, 1, 1); PG8_STAGE(PG8_SB(1, 0), b3, voffB); PG8_STAGE(PG8_SB(1, 1), b3 + hstepB, voffB); PG8_STAGE(PG8_SA(1, 0), a3, voffA);
;             PG8_WAIT_V(8); PG8_WAIT_L(0); PG8_BAR; PG8_MMA(1, 0, At, B0); PG8_MMA(1, 1, At, B1); PG8_BAR; PG8_SCHED;
;         }
;         if constexpr (ALIGN_EPI) { if (wr == 0) PG8_BAR; }
;         if constexpr (!Epi::AFTER_DRAIN) E(acc, cur, wr, wc, fr, fq);
;         if (!has_next) break;
;         if (!(Epi::KEEP_ACC && nxt.z != 0)) {
; #pragma unroll
;         for (int a = 0; a < 2; ++a)
; #pragma unroll
;             for (int b = 0; b < 2; ++b)
; #pragma unroll
;                 for (int m = 0; m < 4; ++m)
; #pragma unroll
;                     for (int n = 0; n < 2; ++n) acc[a][b][m][n] = (f32x4){0.f, 0.f, 0.f, 0.f};
;         }
;         cur = nxt; cA = nA; cB = nB; ++ui;
;         if constexpr (ALIGN_EPI) { if (wr == 1) PG8_BAR; }
;     }
	s_add_i32 s4, s6, s29
	v_lshl_add_u64 v[158:159], v[158:159], 0, s[62:63]
	s_mov_b32 m0, s4
	ds_read_b128 v[192:195], v144 offset:49152
	ds_read_b128 v[214:217], v144 offset:50176
	ds_read_b128 v[218:221], v144 offset:51200
	ds_read_b128 v[222:225], v144 offset:52224
	ds_read_b128 v[226:229], v144 offset:53248
	ds_read_b128 v[230:233], v144 offset:54272
	ds_read_b128 v[234:237], v144 offset:55296
	ds_read_b128 v[238:241], v144 offset:56320
	global_load_lds_dwordx4 v[158:159], off
	v_lshl_add_u64 v[158:159], v[242:243], 0, s[62:63]
	s_add_i32 m0, s4, 0x2000
	s_add_i32 s4, s7, s29
	global_load_lds_dwordx4 v[158:159], off
	v_lshl_add_u64 v[158:159], v[244:245], 0, s[62:63]
	s_mov_b32 m0, s4
	s_nop 0
	global_load_lds_dwordx4 v[158:159], off
	v_lshl_add_u64 v[158:159], v[246:247], 0, s[62:63]
	s_add_i32 m0, s4, 0x2000
	s_nop 0
	global_load_lds_dwordx4 v[158:159], off
	v_lshl_add_u64 v[158:159], v[248:249], 0, s[62:63]
	s_mov_b32 m0, s50
	s_nop 0
	global_load_lds_dwordx4 v[158:159], off
	v_lshl_add_u64 v[158:159], v[250:251], 0, s[62:63]
	s_mov_b32 m0, s51
	s_nop 0
	global_load_lds_dwordx4 v[158:159], off
	s_waitcnt vmcnt(8)
	s_waitcnt lgkmcnt(0)
	s_barrier
	s_setprio 1
	v_mfma_f32_16x16x32_bf16 v[124:127], v[146:149], v[192:195], v[124:127]
	v_mfma_f32_16x16x32_bf16 v[120:123], v[154:157], v[192:195], v[120:123]
	v_mfma_f32_16x16x32_bf16 v[116:119], v[146:149], v[218:221], v[116:119]
	v_mfma_f32_16x16x32_bf16 v[112:115], v[154:157], v[218:221], v[112:115]
	v_mfma_f32_16x16x32_bf16 v[60:63], v[146:149], v[226:229], v[60:63]
	v_mfma_f32_16x16x32_bf16 v[56:59], v[154:157], v[226:229], v[56:59]
	v_mfma_f32_16x16x32_bf16 v[52:55], v[146:149], v[234:237], v[52:55]
	v_mfma_f32_16x16x32_bf16 v[48:51], v[154:157], v[234:237], v[48:51]
	v_mfma_f32_16x16x32_bf16 v[124:127], v[150:153], v[214:217], v[124:127]
	v_mfma_f32_16x16x32_bf16 v[120:123], v[172:175], v[214:217], v[120:123]
	v_mfma_f32_16x16x32_bf16 v[116:119], v[150:153], v[222:225], v[116:119]
	v_mfma_f32_16x16x32_bf16 v[112:115], v[172:175], v[222:225], v[112:115]
	v_mfma_f32_16x16x32_bf16 v[60:63], v[150:153], v[230:233], v[60:63]
	v_mfma_f32_16x16x32_bf16 v[56:59], v[172:175], v[230:233], v[56:59]
	v_mfma_f32_16x16x32_bf16 v[52:55], v[150:153], v[238:241], v[52:55]
	v_mfma_f32_16x16x32_bf16 v[48:51], v[172:175], v[238:241], v[48:51]
	v_mfma_f32_16x16x32_bf16 v[108:111], v[176:179], v[192:195], v[108:111]
	v_mfma_f32_16x16x32_bf16 v[104:107], v[184:187], v[192:195], v[104:107]
	v_mfma_f32_16x16x32_bf16 v[100:103], v[176:179], v[218:221], v[100:103]
	v_mfma_f32_16x16x32_bf16 v[96:99], v[184:187], v[218:221], v[96:99]
	v_mfma_f32_16x16x32_bf16 v[44:47], v[176:179], v[226:229], v[44:47]
	v_mfma_f32_16x16x32_bf16 v[40:43], v[184:187], v[226:229], v[40:43]
	v_mfma_f32_16x16x32_bf16 v[36:39], v[176:179], v[234:237], v[36:39]
	v_mfma_f32_16x16x32_bf16 v[32:35], v[184:187], v[234:237], v[32:35]
	v_mfma_f32_16x16x32_bf16 v[108:111], v[180:183], v[214:217], v[108:111]
	v_mfma_f32_16x16x32_bf16 v[104:107], v[188:191], v[214:217], v[104:107]
	v_mfma_f32_16x16x32_bf16 v[100:103], v[180:183], v[222:225], v[100:103]
	v_mfma_f32_16x16x32_bf16 v[96:99], v[188:191], v[222:225], v[96:99]
	v_mfma_f32_16x16x32_bf16 v[44:47], v[180:183], v[230:233], v[44:47]
	v_mfma_f32_16x16x32_bf16 v[40:43], v[188:191], v[230:233], v[40:43]
	v_mfma_f32_16x16x32_bf16 v[36:39], v[180:183], v[238:241], v[36:39]
	v_mfma_f32_16x16x32_bf16 v[32:35], v[188:191], v[238:241], v[32:35]
	s_setprio 0
	s_barrier
	s_add_u32 vcc_lo, vcc_lo, 0x100
	s_addc_u32 vcc_hi, vcc_hi, 0
	v_lshl_add_u64 v[140:141], v[140:141], 0, s[60:61]
	v_lshl_add_u64 v[138:139], v[138:139], 0, s[60:61]
	s_cmp_ge_u32 s36, s8
	s_mov_b32 s35, s36
	s_cbranch_scc0 .LBB0_172
	s_and_b64 vcc, exec, s[42:43]
	s_cbranch_vccnz .LBB0_160
	v_mov_b32_e32 v32, 0
	s_mov_b32 s66, s30
	s_mov_b32 s9, s31
	s_mov_b64 s[68:69], s[88:89]
	s_mov_b64 s[70:71], s[44:45]
	s_mov_b32 s34, s22
	v_mov_b32_e32 v33, v32
	v_mov_b32_e32 v34, v32
	v_mov_b32_e32 v35, v32
	v_mov_b32_e32 v36, v32
	v_mov_b32_e32 v37, v32
	v_mov_b32_e32 v38, v32
	v_mov_b32_e32 v39, v32
	v_mov_b32_e32 v40, v32
	v_mov_b32_e32 v41, v32
	v_mov_b32_e32 v42, v32
	v_mov_b32_e32 v43, v32
	v_mov_b32_e32 v44, v32
	v_mov_b32_e32 v45, v32
	v_mov_b32_e32 v46, v32
	v_mov_b32_e32 v47, v32
	v_mov_b32_e32 v96, v32
	v_mov_b32_e32 v97, v32
	v_mov_b32_e32 v98, v32
	v_mov_b32_e32 v99, v32
	v_mov_b32_e32 v100, v32
	v_mov_b32_e32 v101, v32
	v_mov_b32_e32 v102, v32
	v_mov_b32_e32 v103, v32
	v_mov_b32_e32 v104, v32
	v_mov_b32_e32 v105, v32
	v_mov_b32_e32 v106, v32
	v_mov_b32_e32 v107, v32
	v_mov_b32_e32 v108, v32
	v_mov_b32_e32 v109, v32
	v_mov_b32_e32 v110, v32
	v_mov_b32_e32 v111, v32
	v_mov_b32_e32 v48, v32
	v_mov_b32_e32 v49, v32
	v_mov_b32_e32 v50, v32
	v_mov_b32_e32 v51, v32
	v_mov_b32_e32 v52, v32
	v_mov_b32_e32 v53, v32
	v_mov_b32_e32 v54, v32
	v_mov_b32_e32 v55, v32
	v_mov_b32_e32 v56, v32
	v_mov_b32_e32 v57, v32
	v_mov_b32_e32 v58, v32
	v_mov_b32_e32 v59, v32
	v_mov_b32_e32 v60, v32
	v_mov_b32_e32 v61, v32
	v_mov_b32_e32 v62, v32
	v_mov_b32_e32 v63, v32
	v_mov_b32_e32 v112, v32
	v_mov_b32_e32 v113, v32
	v_mov_b32_e32 v114, v32
	v_mov_b32_e32 v115, v32
	v_mov_b32_e32 v116, v32
	v_mov_b32_e32 v117, v32
	v_mov_b32_e32 v118, v32
	v_mov_b32_e32 v119, v32
	v_mov_b32_e32 v120, v32
	v_mov_b32_e32 v121, v32
	v_mov_b32_e32 v122, v32
	v_mov_b32_e32 v123, v32
	v_mov_b32_e32 v124, v32
	v_mov_b32_e32 v125, v32
	v_mov_b32_e32 v126, v32
	v_mov_b32_e32 v127, v32
	v_mov_b32_e32 v80, v32
	v_mov_b32_e32 v81, v32
	v_mov_b32_e32 v82, v32
	v_mov_b32_e32 v83, v32
	v_mov_b32_e32 v84, v32
	v_mov_b32_e32 v85, v32
	v_mov_b32_e32 v86, v32
	v_mov_b32_e32 v87, v32
	v_mov_b32_e32 v64, v32
	v_mov_b32_e32 v65, v32
	v_mov_b32_e32 v66, v32
	v_mov_b32_e32 v67, v32
	v_mov_b32_e32 v68, v32
	v_mov_b32_e32 v69, v32
	v_mov_b32_e32 v70, v32
	v_mov_b32_e32 v71, v32
	v_mov_b32_e32 v0, v32
	v_mov_b32_e32 v1, v32
	v_mov_b32_e32 v2, v32
	v_mov_b32_e32 v3, v32
	v_mov_b32_e32 v4, v32
	v_mov_b32_e32 v5, v32
	v_mov_b32_e32 v6, v32
	v_mov_b32_e32 v7, v32
	v_mov_b32_e32 v8, v32
	v_mov_b32_e32 v9, v32
	v_mov_b32_e32 v10, v32
	v_mov_b32_e32 v11, v32
	v_mov_b32_e32 v12, v32
	v_mov_b32_e32 v13, v32
	v_mov_b32_e32 v14, v32
	v_mov_b32_e32 v15, v32
	v_mov_b32_e32 v88, v32
	v_mov_b32_e32 v89, v32
	v_mov_b32_e32 v90, v32
	v_mov_b32_e32 v91, v32
	v_mov_b32_e32 v92, v32
	v_mov_b32_e32 v93, v32
	v_mov_b32_e32 v94, v32
	v_mov_b32_e32 v95, v32
	v_mov_b32_e32 v72, v32
	v_mov_b32_e32 v73, v32
	v_mov_b32_e32 v74, v32
	v_mov_b32_e32 v75, v32
	v_mov_b32_e32 v76, v32
	v_mov_b32_e32 v77, v32
	v_mov_b32_e32 v78, v32
	v_mov_b32_e32 v79, v32
	v_mov_b32_e32 v16, v32
	v_mov_b32_e32 v17, v32
	v_mov_b32_e32 v18, v32
	v_mov_b32_e32 v19, v32
	v_mov_b32_e32 v20, v32
	v_mov_b32_e32 v21, v32
	v_mov_b32_e32 v22, v32
	v_mov_b32_e32 v23, v32
	v_mov_b32_e32 v24, v32
	v_mov_b32_e32 v25, v32
	v_mov_b32_e32 v26, v32
	v_mov_b32_e32 v27, v32
	v_mov_b32_e32 v28, v32
	v_mov_b32_e32 v29, v32
	v_mov_b32_e32 v30, v32
	v_mov_b32_e32 v31, v32
	s_branch .LBB0_160

; #define PG8_STAGE(bufoff, gbase, voff) do { _Pragma("unroll") for (int _i = 0; _i < 2; ++_i) \
;         __builtin_amdgcn_global_load_lds((const unsigned*)((const char*)(gbase) + (voff)[_i]), (LAS unsigned*)(lds + (bufoff) + ldsw + _i * 8192), 16, 0, 0); } while (0)
; #define PG8_LDA(dst, b, h) do { _Pragma("unroll") for (int m = 0; m < 4; ++m) _Pragma("unroll") for (int k = 0; k < 2; ++k) dst[m][k] = *(const LAS bf16x8*)(lds + PG8_SA(b, h) + aoff + m * 2048 + k * 1024); } while (0)
; #define PG8_LDB(dst, b, h) do { _Pragma("unroll") for (int n = 0; n < 2; ++n) _Pragma("unroll") for (int k = 0; k < 2; ++k) dst[n][k] = *(const LAS bf16x8*)(lds + PG8_SB(b, h) + boff + n * 2048 + k * 1024); } while (0)
; #define PG8_WAIT_V(n) asm volatile("s_waitcnt vmcnt(" #n ")" ::: "memory")
; #define PG8_WAIT_L(n) asm volatile("s_waitcnt lgkmcnt(" #n ")" ::: "memory")
; #define PG8_BAR __builtin_amdgcn_s_barrier()
; #define PG8_SCHED __builtin_amdgcn_sched_barrier(0)
; template <class Epi>
; __device__ __forceinline__ void gemm_phase(LAS unsigned char* lds, const Gemm g, const Order& S, const Epi& E) {
;     ...
;         const bool has_next = S.next(ui + 1, nxt);
;         const char* nA = has_next ? (const char*)(g.A + (size_t)nxt.pm * BM * g.lda + (size_t)nxt.z * g.za) : cA;
;         const char* nB = has_next ? (const char*)(g.Bt + (size_t)nxt.pn * BM * g.ldb + (size_t)nxt.z * g.zb) : cB;
;         for (int t = 0; t < nt; t += 2) {
;             const bool last = (t == nt - 2);
;             const char* a1 = cA + (size_t)(t + 1) * kstep;
;             const char* a2 = last ? nA : cA + (size_t)(t + 2) * kstep; const char* b2 = last ? nB : cB + (size_t)(t + 2) * kstep;
;             const char* a3 = a2 + kstep; const char* b3 = b2 + kstep;
;             PG8_LDB(B0, 0, 0); PG8_LDB(B1, 0, 1); PG8_SCHED; PG8_LDA(At, 0, 0); PG8_STAGE(PG8_SA(1, 1), a1 + hstepA, voffA);
;             PG8_WAIT_V(8); PG8_WAIT_L(0); PG8_BAR; PG8_MMA(0, 0, At, B0); PG8_MMA(0, 1, At, B1); PG8_BAR; PG8_SCHED;
;             PG8_LDA(At, 0, 1); PG8_STAGE(PG8_SB(0, 0), b2, voffB); PG8_STAGE(PG8_SB(0, 1), b2 + hstepB, voffB); PG8_STAGE(PG8_SA(0, 0), a2, voffA);
;             PG8_WAIT_V(8); PG8_WAIT_L(0); PG8_BAR; PG8_MMA(1, 0, At, B0); PG8_MMA(1, 1, At, B1); PG8_BAR; PG8_SCHED;
.LBB0_281:
	s_add_u32 s40, s64, 0x100
	s_addc_u32 s41, s65, 0
	s_add_i32 s4, 0, 0x10000
	s_cmp_eq_u32 s47, 4
	s_cselect_b32 s69, s49, s41
	s_cselect_b32 s68, s48, s40
	s_cselect_b32 s67, s34, s45
	s_cselect_b32 s66, s35, s43
	s_add_i32 s6, 0, 0x14000
	v_add_u32_e32 v150, s4, v184
	v_add_u32_e32 v158, s6, v184
	ds_read_b128 v[138:141], v150
	ds_read_b128 v[142:145], v150 offset:1024
	ds_read_b128 v[146:149], v150 offset:2048
	ds_read_b128 v[150:153], v150 offset:3072
	ds_read_b128 v[154:157], v158
	ds_read_b128 v[172:175], v158 offset:1024
	ds_read_b128 v[176:179], v158 offset:2048
	ds_read_b128 v[180:183], v158 offset:3072
	v_lshl_add_u64 v[158:159], s[64:65], 0, v[134:135]
	s_add_i32 m0, s25, 0xc000
	ds_read_b128 v[188:191], v186
	ds_read_b128 v[192:195], v186 offset:1024
	ds_read_b128 v[214:217], v186 offset:2048
	ds_read_b128 v[218:221], v186 offset:3072
	ds_read_b128 v[222:225], v186 offset:4096
	ds_read_b128 v[226:229], v186 offset:5120
	ds_read_b128 v[230:233], v186 offset:6144
	ds_read_b128 v[234:237], v186 offset:7168
	global_load_lds_dwordx4 v[158:159], off
	v_lshl_add_u64 v[158:159], s[64:65], 0, v[136:137]
	s_add_i32 m0, s25, 0xe000
	s_nop 0
	global_load_lds_dwordx4 v[158:159], off
	s_waitcnt vmcnt(8)
	s_waitcnt lgkmcnt(0)
	s_barrier
	s_setprio 1
	v_mfma_f32_16x16x32_bf16 v[124:127], v[138:141], v[188:191], v[124:127]
	v_mfma_f32_16x16x32_bf16 v[120:123], v[146:149], v[188:191], v[120:123]
	v_mfma_f32_16x16x32_bf16 v[116:119], v[138:141], v[214:217], v[116:119]
	v_mfma_f32_16x16x32_bf16 v[112:115], v[146:149], v[214:217], v[112:115]
	v_mfma_f32_16x16x32_bf16 v[108:111], v[138:141], v[222:225], v[108:111]
	v_mfma_f32_16x16x32_bf16 v[104:107], v[146:149], v[222:225], v[104:107]
	v_mfma_f32_16x16x32_bf16 v[100:103], v[138:141], v[230:233], v[100:103]
	v_mfma_f32_16x16x32_bf16 v[96:99], v[146:149], v[230:233], v[96:99]
	v_mfma_f32_16x16x32_bf16 v[124:127], v[142:145], v[192:195], v[124:127]
	v_mfma_f32_16x16x32_bf16 v[120:123], v[150:153], v[192:195], v[120:123]
	v_mfma_f32_16x16x32_bf16 v[116:119], v[142:145], v[218:221], v[116:119]
	v_mfma_f32_16x16x32_bf16 v[112:115], v[150:153], v[218:221], v[112:115]
	v_mfma_f32_16x16x32_bf16 v[108:111], v[142:145], v[226:229], v[108:111]
	v_mfma_f32_16x16x32_bf16 v[104:107], v[150:153], v[226:229], v[104:107]
	v_mfma_f32_16x16x32_bf16 v[100:103], v[142:145], v[234:237], v[100:103]
	v_mfma_f32_16x16x32_bf16 v[96:99], v[150:153], v[234:237], v[96:99]
	v_mfma_f32_16x16x32_bf16 v[92:95], v[154:157], v[188:191], v[92:95]
	v_mfma_f32_16x16x32_bf16 v[88:91], v[176:179], v[188:191], v[88:91]
	v_mfma_f32_16x16x32_bf16 v[84:87], v[154:157], v[214:217], v[84:87]
	v_mfma_f32_16x16x32_bf16 v[80:83], v[176:179], v[214:217], v[80:83]
	v_mfma_f32_16x16x32_bf16 v[76:79], v[154:157], v[222:225], v[76:79]
	v_mfma_f32_16x16x32_bf16 v[72:75], v[176:179], v[222:225], v[72:75]
	v_mfma_f32_16x16x32_bf16 v[68:71], v[154:157], v[230:233], v[68:71]
	v_mfma_f32_16x16x32_bf16 v[64:67], v[176:179], v[230:233], v[64:67]
	v_mfma_f32_16x16x32_bf16 v[92:95], v[172:175], v[192:195], v[92:95]
	v_mfma_f32_16x16x32_bf16 v[88:91], v[180:183], v[192:195], v[88:91]
	v_mfma_f32_16x16x32_bf16 v[84:87], v[172:175], v[218:221], v[84:87]
	v_mfma_f32_16x16x32_bf16 v[80:83], v[180:183], v[218:221], v[80:83]
	v_mfma_f32_16x16x32_bf16 v[76:79], v[172:175], v[226:229], v[76:79]
	v_mfma_f32_16x16x32_bf16 v[72:75], v[180:183], v[226:229], v[72:75]
	v_mfma_f32_16x16x32_bf16 v[68:71], v[172:175], v[234:237], v[68:71]
	v_mfma_f32_16x16x32_bf16 v[64:67], v[180:183], v[234:237], v[64:67]
	s_setprio 0
	s_barrier
	s_add_i32 s4, s4, s24
	v_lshl_add_u64 v[158:159], s[66:67], 0, v[160:161]
	s_mov_b32 m0, s4
	ds_read_b128 v[188:191], v186 offset:16384
	ds_read_b128 v[192:195], v186 offset:17408
	ds_read_b128 v[214:217], v186 offset:18432
	ds_read_b128 v[218:221], v186 offset:19456
	ds_read_b128 v[222:225], v186 offset:20480
	ds_read_b128 v[226:229], v186 offset:21504
	ds_read_b128 v[230:233], v186 offset:22528
	ds_read_b128 v[234:237], v186 offset:23552
	global_load_lds_dwordx4 v[158:159], off
	s_add_i32 m0, s4, 0x2000
	s_add_u32 s4, s66, 0x20000
	v_lshl_add_u64 v[200:201], s[66:67], 0, v[128:129]
	s_addc_u32 s5, s67, 0
	s_add_i32 s6, s6, s24
	global_load_lds_dwordx4 v[200:201], off
	v_lshl_add_u64 v[238:239], s[4:5], 0, v[160:161]
	s_mov_b32 m0, s6
	v_lshl_add_u64 v[240:241], s[68:69], 0, v[130:131]
	global_load_lds_dwordx4 v[238:239], off
	v_lshl_add_u64 v[238:239], s[4:5], 0, v[128:129]
	s_add_i32 m0, s6, 0x2000
	s_nop 0
	global_load_lds_dwordx4 v[238:239], off
	v_lshl_add_u64 v[238:239], s[68:69], 0, v[132:133]
	s_mov_b32 m0, s25
	s_nop 0
	global_load_lds_dwordx4 v[238:239], off
	s_mov_b32 m0, s26
	s_nop 0
	global_load_lds_dwordx4 v[240:241], off
	s_waitcnt vmcnt(8)
	s_waitcnt lgkmcnt(0)
	s_barrier
; #define PG8_STAGE(bufoff, gbase, voff) do { _Pragma("unroll") for (int _i = 0; _i < 2; ++_i) \
;         __builtin_amdgcn_global_load_lds((const unsigned*)((const char*)(gbase) + (voff)[_i]), (LAS unsigned*)(lds + (bufoff) + ldsw + _i * 8192), 16, 0, 0); } while (0)
; #define PG8_LDA(dst, b, h) do { _Pragma("unroll") for (int m = 0; m < 4; ++m) _Pragma("unroll") for (int k = 0; k < 2; ++k) dst[m][k] = *(const LAS bf16x8*)(lds + PG8_SA(b, h) + aoff + m * 2048 + k * 1024); } while (0)
; #define PG8_LDB(dst, b, h) do { _Pragma("unroll") for (int n = 0; n < 2; ++n) _Pragma("unroll") for (int k = 0; k < 2; ++k) dst[n][k] = *(const LAS bf16x8*)(lds + PG8_SB(b, h) + boff + n * 2048 + k * 1024); } while (0)
; #define PG8_WAIT_V(n) asm volatile("s_waitcnt vmcnt(" #n ")" ::: "memory")
; #define PG8_WAIT_L(n) asm volatile("s_waitcnt lgkmcnt(" #n ")" ::: "memory")
; #define PG8_BAR __builtin_amdgcn_s_barrier()
; #define PG8_SCHED __builtin_amdgcn_sched_barrier(0)
; template <class Epi>
; __device__ __forceinline__ void gemm_phase(LAS unsigned char* lds, const Gemm g, const Order& S, const Epi& E) {
;     ...
;             PG8_WAIT_V(8); PG8_WAIT_L(0); PG8_BAR; PG8_MMA(1, 0, At, B0); PG8_MMA(1, 1, At, B1); PG8_BAR; PG8_SCHED;
;             PG8_LDB(B0, 1, 0); PG8_LDB(B1, 1, 1); PG8_SCHED; PG8_LDA(At, 1, 0); PG8_STAGE(PG8_SA(0, 1), a2 + hstepA, voffA);
;             PG8_WAIT_V(8); PG8_WAIT_L(0); PG8_BAR; PG8_MMA(0, 0, At, B0); PG8_MMA(0, 1, At, B1); PG8_BAR; PG8_SCHED;
	s_setprio 1
	v_mfma_f32_16x16x32_bf16 v[60:63], v[138:141], v[188:191], v[60:63]
	v_mfma_f32_16x16x32_bf16 v[56:59], v[146:149], v[188:191], v[56:59]
	v_mfma_f32_16x16x32_bf16 v[52:55], v[138:141], v[214:217], v[52:55]
	v_mfma_f32_16x16x32_bf16 v[48:51], v[146:149], v[214:217], v[48:51]
	v_mfma_f32_16x16x32_bf16 v[44:47], v[138:141], v[222:225], v[44:47]
	v_mfma_f32_16x16x32_bf16 v[40:43], v[146:149], v[222:225], v[40:43]
	v_mfma_f32_16x16x32_bf16 v[36:39], v[138:141], v[230:233], v[36:39]
	v_mfma_f32_16x16x32_bf16 v[32:35], v[146:149], v[230:233], v[32:35]
	v_mfma_f32_16x16x32_bf16 v[60:63], v[142:145], v[192:195], v[60:63]
	v_mfma_f32_16x16x32_bf16 v[56:59], v[150:153], v[192:195], v[56:59]
	v_mfma_f32_16x16x32_bf16 v[52:55], v[142:145], v[218:221], v[52:55]
	v_mfma_f32_16x16x32_bf16 v[48:51], v[150:153], v[218:221], v[48:51]
	v_mfma_f32_16x16x32_bf16 v[44:47], v[142:145], v[226:229], v[44:47]
	v_mfma_f32_16x16x32_bf16 v[40:43], v[150:153], v[226:229], v[40:43]
	v_mfma_f32_16x16x32_bf16 v[36:39], v[142:145], v[234:237], v[36:39]
	v_mfma_f32_16x16x32_bf16 v[32:35], v[150:153], v[234:237], v[32:35]
	v_mfma_f32_16x16x32_bf16 v[28:31], v[154:157], v[188:191], v[28:31]
	v_mfma_f32_16x16x32_bf16 v[24:27], v[176:179], v[188:191], v[24:27]
	v_mfma_f32_16x16x32_bf16 v[20:23], v[154:157], v[214:217], v[20:23]
	v_mfma_f32_16x16x32_bf16 v[16:19], v[176:179], v[214:217], v[16:19]
	v_mfma_f32_16x16x32_bf16 v[12:15], v[154:157], v[222:225], v[12:15]
	v_mfma_f32_16x16x32_bf16 v[8:11], v[176:179], v[222:225], v[8:11]
	v_mfma_f32_16x16x32_bf16 v[4:7], v[154:157], v[230:233], v[4:7]
	v_mfma_f32_16x16x32_bf16 v[0:3], v[176:179], v[230:233], v[0:3]
	v_mfma_f32_16x16x32_bf16 v[28:31], v[172:175], v[192:195], v[28:31]
	v_mfma_f32_16x16x32_bf16 v[24:27], v[180:183], v[192:195], v[24:27]
	v_mfma_f32_16x16x32_bf16 v[20:23], v[172:175], v[218:221], v[20:23]
	v_mfma_f32_16x16x32_bf16 v[16:19], v[180:183], v[218:221], v[16:19]
	v_mfma_f32_16x16x32_bf16 v[12:15], v[172:175], v[226:229], v[12:15]
	v_mfma_f32_16x16x32_bf16 v[8:11], v[180:183], v[226:229], v[8:11]
	v_mfma_f32_16x16x32_bf16 v[4:7], v[172:175], v[234:237], v[4:7]
	v_mfma_f32_16x16x32_bf16 v[0:3], v[180:183], v[234:237], v[0:3]
	s_setprio 0
	s_barrier
	s_add_i32 s6, 0, 0x18000
	s_add_i32 s7, 0, 0x1c000
	v_add_u32_e32 v150, s6, v184
	v_add_u32_e32 v180, s7, v184
	ds_read_b128 v[138:141], v150
	ds_read_b128 v[142:145], v150 offset:1024
	ds_read_b128 v[146:149], v150 offset:2048
	ds_read_b128 v[150:153], v150 offset:3072
	ds_read_b128 v[154:157], v180
	ds_read_b128 v[172:175], v180 offset:1024
	ds_read_b128 v[176:179], v180 offset:2048
	ds_read_b128 v[180:183], v180 offset:3072
	s_add_u32 s4, s68, 0x60000
	s_addc_u32 s5, s69, 0
	s_mov_b32 m0, s27
	v_lshl_add_u64 v[242:243], s[4:5], 0, v[132:133]
	ds_read_b128 v[188:191], v186 offset:32768
	ds_read_b128 v[192:195], v186 offset:33792
	ds_read_b128 v[214:217], v186 offset:34816
	ds_read_b128 v[218:221], v186 offset:35840
	ds_read_b128 v[222:225], v186 offset:36864
	ds_read_b128 v[226:229], v186 offset:37888
	ds_read_b128 v[230:233], v186 offset:38912
	ds_read_b128 v[234:237], v186 offset:39936
	global_load_lds_dwordx4 v[242:243], off
	v_lshl_add_u64 v[242:243], s[4:5], 0, v[130:131]
	s_mov_b32 m0, s28
	s_nop 0
	global_load_lds_dwordx4 v[242:243], off
	s_waitcnt vmcnt(8)
	s_waitcnt lgkmcnt(0)
	s_barrier
	s_setprio 1
	v_mfma_f32_16x16x32_bf16 v[124:127], v[138:141], v[188:191], v[124:127]
	v_mfma_f32_16x16x32_bf16 v[120:123], v[146:149], v[188:191], v[120:123]
	v_mfma_f32_16x16x32_bf16 v[116:119], v[138:141], v[214:217], v[116:119]
	v_mfma_f32_16x16x32_bf16 v[112:115], v[146:149], v[214:217], v[112:115]
	v_mfma_f32_16x16x32_bf16 v[108:111], v[138:141], v[222:225], v[108:111]
	v_mfma_f32_16x16x32_bf16 v[104:107], v[146:149], v[222:225], v[104:107]
	v_mfma_f32_16x16x32_bf16 v[100:103], v[138:141], v[230:233], v[100:103]
	v_mfma_f32_16x16x32_bf16 v[96:99], v[146:149], v[230:233], v[96:99]
	v_mfma_f32_16x16x32_bf16 v[124:127], v[142:145], v[192:195], v[124:127]
	v_mfma_f32_16x16x32_bf16 v[120:123], v[150:153], v[192:195], v[120:123]
	v_mfma_f32_16x16x32_bf16 v[116:119], v[142:145], v[218:221], v[116:119]
	v_mfma_f32_16x16x32_bf16 v[112:115], v[150:153], v[218:221], v[112:115]
	v_mfma_f32_16x16x32_bf16 v[108:111], v[142:145], v[226:229], v[108:111]
	v_mfma_f32_16x16x32_bf16 v[104:107], v[150:153], v[226:229], v[104:107]
	v_mfma_f32_16x16x32_bf16 v[100:103], v[142:145], v[234:237], v[100:103]
	v_mfma_f32_16x16x32_bf16 v[96:99], v[150:153], v[234:237], v[96:99]
	v_mfma_f32_16x16x32_bf16 v[92:95], v[154:157], v[188:191], v[92:95]
	v_mfma_f32_16x16x32_bf16 v[88:91], v[176:179], v[188:191], v[88:91]
	v_mfma_f32_16x16x32_bf16 v[84:87], v[154:157], v[214:217], v[84:87]
	v_mfma_f32_16x16x32_bf16 v[80:83], v[176:179], v[214:217], v[80:83]
	v_mfma_f32_16x16x32_bf16 v[76:79], v[154:157], v[222:225], v[76:79]
	v_mfma_f32_16x16x32_bf16 v[72:75], v[176:179], v[222:225], v[72:75]
	v_mfma_f32_16x16x32_bf16 v[68:71], v[154:157], v[230:233], v[68:71]
	v_mfma_f32_16x16x32_bf16 v[64:67], v[176:179], v[230:233], v[64:67]
	v_mfma_f32_16x16x32_bf16 v[92:95], v[172:175], v[192:195], v[92:95]
	v_mfma_f32_16x16x32_bf16 v[88:91], v[180:183], v[192:195], v[88:91]
	v_mfma_f32_16x16x32_bf16 v[84:87], v[172:175], v[218:221], v[84:87]
	v_mfma_f32_16x16x32_bf16 v[80:83], v[180:183], v[218:221], v[80:83]
	v_mfma_f32_16x16x32_bf16 v[76:79], v[172:175], v[226:229], v[76:79]
	v_mfma_f32_16x16x32_bf16 v[72:75], v[180:183], v[226:229], v[72:75]
	v_mfma_f32_16x16x32_bf16 v[68:71], v[172:175], v[234:237], v[68:71]
	v_mfma_f32_16x16x32_bf16 v[64:67], v[180:183], v[234:237], v[64:67]
	s_setprio 0
	s_barrier
; #define PG8_STAGE(bufoff, gbase, voff) do { _Pragma("unroll") for (int _i = 0; _i < 2; ++_i) \
;         __builtin_amdgcn_global_load_lds((const unsigned*)((const char*)(gbase) + (voff)[_i]), (LAS unsigned*)(lds + (bufoff) + ldsw + _i * 8192), 16, 0, 0); } while (0)
; #define PG8_LDA(dst, b, h) do { _Pragma("unroll") for (int m = 0; m < 4; ++m) _Pragma("unroll") for (int k = 0; k < 2; ++k) dst[m][k] = *(const LAS bf16x8*)(lds + PG8_SA(b, h) + aoff + m * 2048 + k * 1024); } while (0)
; #define PG8_WAIT_V(n) asm volatile("s_waitcnt vmcnt(" #n ")" ::: "memory")
; #define PG8_WAIT_L(n) asm volatile("s_waitcnt lgkmcnt(" #n ")" ::: "memory")
; #define PG8_BAR __builtin_amdgcn_s_barrier()
; #define PG8_SCHED __builtin_amdgcn_sched_barrier(0)
; template <class Epi>
; __device__ __forceinline__ void gemm_phase(LAS unsigned char* lds, const Gemm g, const Order& S, const Epi& E) {
;     ...
;             PG8_LDA(At, 1, 1); PG8_STAGE(PG8_SB(1, 0), b3, voffB); PG8_STAGE(PG8_SB(1, 1), b3 + hstepB, voffB); PG8_STAGE(PG8_SA(1, 0), a3, voffA);
;             PG8_WAIT_V(8); PG8_WAIT_L(0); PG8_BAR; PG8_MMA(1, 0, At, B0); PG8_MMA(1, 1, At, B1); PG8_BAR; PG8_SCHED;
;         }
;         if constexpr (ALIGN_EPI) { if (wr == 0) PG8_BAR; }
;         if constexpr (!Epi::AFTER_DRAIN) E(acc, cur, wr, wc, fr, fq);
;         if (!has_next) break;
	s_add_i32 s4, s6, s24
	v_lshl_add_u64 v[158:159], v[158:159], 0, s[62:63]
	s_mov_b32 m0, s4
	ds_read_b128 v[188:191], v186 offset:49152
	ds_read_b128 v[192:195], v186 offset:50176
	ds_read_b128 v[214:217], v186 offset:51200
	ds_read_b128 v[218:221], v186 offset:52224
	ds_read_b128 v[222:225], v186 offset:53248
	ds_read_b128 v[226:229], v186 offset:54272
	ds_read_b128 v[230:233], v186 offset:55296
	ds_read_b128 v[234:237], v186 offset:56320
	global_load_lds_dwordx4 v[158:159], off
	s_add_i32 m0, s4, 0x2000
	s_add_u32 s4, s66, 0x20080
	v_lshl_add_u64 v[158:159], v[200:201], 0, s[62:63]
	s_addc_u32 s5, s67, 0
	s_add_i32 s6, s7, s24
	global_load_lds_dwordx4 v[158:159], off
	v_lshl_add_u64 v[158:159], s[4:5], 0, v[160:161]
	s_mov_b32 m0, s6
	s_nop 0
	global_load_lds_dwordx4 v[158:159], off
	v_lshl_add_u64 v[158:159], s[4:5], 0, v[128:129]
	s_add_i32 m0, s6, 0x2000
	s_nop 0
	global_load_lds_dwordx4 v[158:159], off
	v_lshl_add_u64 v[158:159], v[238:239], 0, s[62:63]
	s_mov_b32 m0, s29
	s_nop 0
	global_load_lds_dwordx4 v[158:159], off
	v_lshl_add_u64 v[158:159], v[240:241], 0, s[62:63]
	s_mov_b32 m0, s70
	s_nop 0
	global_load_lds_dwordx4 v[158:159], off
	s_waitcnt vmcnt(8)
	s_waitcnt lgkmcnt(0)
	s_barrier
	s_setprio 1
	v_mfma_f32_16x16x32_bf16 v[60:63], v[138:141], v[188:191], v[60:63]
	v_mfma_f32_16x16x32_bf16 v[56:59], v[146:149], v[188:191], v[56:59]
	v_mfma_f32_16x16x32_bf16 v[52:55], v[138:141], v[214:217], v[52:55]
	v_mfma_f32_16x16x32_bf16 v[48:51], v[146:149], v[214:217], v[48:51]
	v_mfma_f32_16x16x32_bf16 v[44:47], v[138:141], v[222:225], v[44:47]
	v_mfma_f32_16x16x32_bf16 v[40:43], v[146:149], v[222:225], v[40:43]
	v_mfma_f32_16x16x32_bf16 v[36:39], v[138:141], v[230:233], v[36:39]
	v_mfma_f32_16x16x32_bf16 v[32:35], v[146:149], v[230:233], v[32:35]
	v_mfma_f32_16x16x32_bf16 v[60:63], v[142:145], v[192:195], v[60:63]
	v_mfma_f32_16x16x32_bf16 v[56:59], v[150:153], v[192:195], v[56:59]
	v_mfma_f32_16x16x32_bf16 v[52:55], v[142:145], v[218:221], v[52:55]
	v_mfma_f32_16x16x32_bf16 v[48:51], v[150:153], v[218:221], v[48:51]
	v_mfma_f32_16x16x32_bf16 v[44:47], v[142:145], v[226:229], v[44:47]
	v_mfma_f32_16x16x32_bf16 v[40:43], v[150:153], v[226:229], v[40:43]
	v_mfma_f32_16x16x32_bf16 v[36:39], v[142:145], v[234:237], v[36:39]
	v_mfma_f32_16x16x32_bf16 v[32:35], v[150:153], v[234:237], v[32:35]
	v_mfma_f32_16x16x32_bf16 v[28:31], v[154:157], v[188:191], v[28:31]
	v_mfma_f32_16x16x32_bf16 v[24:27], v[176:179], v[188:191], v[24:27]
	v_mfma_f32_16x16x32_bf16 v[20:23], v[154:157], v[214:217], v[20:23]
	v_mfma_f32_16x16x32_bf16 v[16:19], v[176:179], v[214:217], v[16:19]
	v_mfma_f32_16x16x32_bf16 v[12:15], v[154:157], v[222:225], v[12:15]
	v_mfma_f32_16x16x32_bf16 v[8:11], v[176:179], v[222:225], v[8:11]
	v_mfma_f32_16x16x32_bf16 v[4:7], v[154:157], v[230:233], v[4:7]
	v_mfma_f32_16x16x32_bf16 v[0:3], v[176:179], v[230:233], v[0:3]
	v_mfma_f32_16x16x32_bf16 v[28:31], v[172:175], v[192:195], v[28:31]
	v_mfma_f32_16x16x32_bf16 v[24:27], v[180:183], v[192:195], v[24:27]
	v_mfma_f32_16x16x32_bf16 v[20:23], v[172:175], v[218:221], v[20:23]
	v_mfma_f32_16x16x32_bf16 v[16:19], v[180:183], v[218:221], v[16:19]
	v_mfma_f32_16x16x32_bf16 v[12:15], v[172:175], v[226:229], v[12:15]
	v_mfma_f32_16x16x32_bf16 v[8:11], v[180:183], v[226:229], v[8:11]
	v_mfma_f32_16x16x32_bf16 v[4:7], v[172:175], v[234:237], v[4:7]
	v_mfma_f32_16x16x32_bf16 v[0:3], v[180:183], v[234:237], v[0:3]
	s_setprio 0
	s_barrier
	s_add_i32 s47, s47, 2
	s_add_u32 s43, s43, 0x100
	s_addc_u32 s45, s45, 0
	s_cmp_gt_u32 s47, 5
	s_mov_b64 s[64:65], s[40:41]
	s_cbranch_scc0 .LBB0_281
	s_and_b64 vcc, exec, s[12:13]
	s_cbranch_vccz .LBB0_284
	s_barrier

; #define PG8_STAGE(bufoff, gbase, voff) do { _Pragma("unroll") for (int _i = 0; _i < 2; ++_i) \
;         __builtin_amdgcn_global_load_lds((const unsigned*)((const char*)(gbase) + (voff)[_i]), (LAS unsigned*)(lds + (bufoff) + ldsw + _i * 8192), 16, 0, 0); } while (0)
; #define PG8_LDA(dst, b, h) do { _Pragma("unroll") for (int m = 0; m < 4; ++m) _Pragma("unroll") for (int k = 0; k < 2; ++k) dst[m][k] = *(const LAS bf16x8*)(lds + PG8_SA(b, h) + aoff + m * 2048 + k * 1024); } while (0)
; #define PG8_LDB(dst, b, h) do { _Pragma("unroll") for (int n = 0; n < 2; ++n) _Pragma("unroll") for (int k = 0; k < 2; ++k) dst[n][k] = *(const LAS bf16x8*)(lds + PG8_SB(b, h) + boff + n * 2048 + k * 1024); } while (0)
; #define PG8_WAIT_V(n) asm volatile("s_waitcnt vmcnt(" #n ")" ::: "memory")
; #define PG8_WAIT_L(n) asm volatile("s_waitcnt lgkmcnt(" #n ")" ::: "memory")
; #define PG8_BAR __builtin_amdgcn_s_barrier()
; #define PG8_SCHED __builtin_amdgcn_sched_barrier(0)
; template <class Epi>
; __device__ __forceinline__ void gemm_phase(LAS unsigned char* lds, const Gemm g, const Order& S, const Epi& E) {
;     ...
;         const bool has_next = S.next(ui + 1, nxt);
;         const char* nA = has_next ? (const char*)(g.A + (size_t)nxt.pm * BM * g.lda + (size_t)nxt.z * g.za) : cA;
;         const char* nB = has_next ? (const char*)(g.Bt + (size_t)nxt.pn * BM * g.ldb + (size_t)nxt.z * g.zb) : cB;
;         for (int t = 0; t < nt; t += 2) {
;             const bool last = (t == nt - 2);
;             const char* a1 = cA + (size_t)(t + 1) * kstep;
;             const char* a2 = last ? nA : cA + (size_t)(t + 2) * kstep; const char* b2 = last ? nB : cB + (size_t)(t + 2) * kstep;
;             const char* a3 = a2 + kstep; const char* b3 = b2 + kstep;
;             PG8_LDB(B0, 0, 0); PG8_LDB(B1, 0, 1); PG8_SCHED; PG8_LDA(At, 0, 0); PG8_STAGE(PG8_SA(1, 1), a1 + hstepA, voffA);
;             PG8_WAIT_V(8); PG8_WAIT_L(0); PG8_BAR; PG8_MMA(0, 0, At, B0); PG8_MMA(0, 1, At, B1); PG8_BAR; PG8_SCHED;
;             PG8_LDA(At, 0, 1); PG8_STAGE(PG8_SB(0, 0), b2, voffB); PG8_STAGE(PG8_SB(0, 1), b2 + hstepB, voffB); PG8_STAGE(PG8_SA(0, 0), a2, voffA);
;             PG8_WAIT_V(8); PG8_WAIT_L(0); PG8_BAR; PG8_MMA(1, 0, At, B0); PG8_MMA(1, 1, At, B1); PG8_BAR; PG8_SCHED;
.LBB0_396:
	s_add_u32 s4, s50, 0xfffc0080
	s_addc_u32 s5, s51, -1
	s_add_i32 s36, 0, 0x10000
	s_cmp_eq_u32 s71, 12
	s_cselect_b32 s67, s34, s5
	s_cselect_b32 s66, s35, s4
	v_add_u32_e32 v138, s36, v141
	s_cselect_b32 s65, s43, s70
	s_cselect_b32 s64, s45, s69
	s_add_i32 s4, 0, 0x14000
	ds_read_b128 v[144:147], v138
	ds_read_b128 v[148:151], v138 offset:1024
	ds_read_b128 v[152:155], v138 offset:2048
	ds_read_b128 v[156:159], v138 offset:3072
	v_add_u32_e32 v138, s4, v141
	ds_read_b128 v[172:175], v138
	ds_read_b128 v[176:179], v138 offset:1024
	ds_read_b128 v[180:183], v138 offset:2048
	ds_read_b128 v[184:187], v138 offset:3072
	v_lshl_add_u64 v[138:139], s[50:51], 0, v[134:135]
	s_add_i32 m0, s24, 0xc000
	ds_read_b128 v[188:191], v143
	ds_read_b128 v[192:195], v143 offset:1024
	ds_read_b128 v[214:217], v143 offset:2048
	ds_read_b128 v[218:221], v143 offset:3072
	ds_read_b128 v[222:225], v143 offset:4096
	ds_read_b128 v[226:229], v143 offset:5120
	ds_read_b128 v[230:233], v143 offset:6144
	ds_read_b128 v[234:237], v143 offset:7168
	global_load_lds_dwordx4 v[138:139], off
	v_lshl_add_u64 v[138:139], s[50:51], 0, v[136:137]
	s_add_i32 m0, s24, 0xe000
	s_nop 0
	global_load_lds_dwordx4 v[138:139], off
	s_waitcnt vmcnt(8)
	s_waitcnt lgkmcnt(0)
	s_barrier
	s_setprio 1
	v_mfma_f32_16x16x32_f16 v[124:127], v[144:147], v[188:191], v[124:127]
	v_mfma_f32_16x16x32_f16 v[112:115], v[152:155], v[188:191], v[112:115]
	v_mfma_f32_16x16x32_f16 v[108:111], v[144:147], v[214:217], v[108:111]
	v_mfma_f32_16x16x32_f16 v[96:99], v[152:155], v[214:217], v[96:99]
	v_mfma_f32_16x16x32_f16 v[92:95], v[144:147], v[222:225], v[92:95]
	v_mfma_f32_16x16x32_f16 v[80:83], v[152:155], v[222:225], v[80:83]
	v_mfma_f32_16x16x32_f16 v[76:79], v[144:147], v[230:233], v[76:79]
	v_mfma_f32_16x16x32_f16 v[64:67], v[152:155], v[230:233], v[64:67]
	v_mfma_f32_16x16x32_f16 v[124:127], v[148:151], v[192:195], v[124:127]
	v_mfma_f32_16x16x32_f16 v[112:115], v[156:159], v[192:195], v[112:115]
	v_mfma_f32_16x16x32_f16 v[108:111], v[148:151], v[218:221], v[108:111]
	v_mfma_f32_16x16x32_f16 v[96:99], v[156:159], v[218:221], v[96:99]
	v_mfma_f32_16x16x32_f16 v[92:95], v[148:151], v[226:229], v[92:95]
	v_mfma_f32_16x16x32_f16 v[80:83], v[156:159], v[226:229], v[80:83]
	v_mfma_f32_16x16x32_f16 v[76:79], v[148:151], v[234:237], v[76:79]
	v_mfma_f32_16x16x32_f16 v[64:67], v[156:159], v[234:237], v[64:67]
	v_mfma_f32_16x16x32_f16 v[120:123], v[172:175], v[188:191], v[120:123]
	v_mfma_f32_16x16x32_f16 v[116:119], v[180:183], v[188:191], v[116:119]
	v_mfma_f32_16x16x32_f16 v[104:107], v[172:175], v[214:217], v[104:107]
	v_mfma_f32_16x16x32_f16 v[100:103], v[180:183], v[214:217], v[100:103]
	v_mfma_f32_16x16x32_f16 v[88:91], v[172:175], v[222:225], v[88:91]
	v_mfma_f32_16x16x32_f16 v[84:87], v[180:183], v[222:225], v[84:87]
	v_mfma_f32_16x16x32_f16 v[72:75], v[172:175], v[230:233], v[72:75]
	v_mfma_f32_16x16x32_f16 v[68:71], v[180:183], v[230:233], v[68:71]
	v_mfma_f32_16x16x32_f16 v[120:123], v[176:179], v[192:195], v[120:123]
	v_mfma_f32_16x16x32_f16 v[116:119], v[184:187], v[192:195], v[116:119]
	v_mfma_f32_16x16x32_f16 v[104:107], v[176:179], v[218:221], v[104:107]
	v_mfma_f32_16x16x32_f16 v[100:103], v[184:187], v[218:221], v[100:103]
	v_mfma_f32_16x16x32_f16 v[88:91], v[176:179], v[226:229], v[88:91]
	v_mfma_f32_16x16x32_f16 v[84:87], v[184:187], v[226:229], v[84:87]
	v_mfma_f32_16x16x32_f16 v[72:75], v[176:179], v[234:237], v[72:75]
	v_mfma_f32_16x16x32_f16 v[68:71], v[184:187], v[234:237], v[68:71]
	s_setprio 0
	s_barrier
	s_add_i32 s5, s36, s23
	v_lshl_add_u64 v[138:139], s[64:65], 0, v[160:161]
	s_mov_b32 m0, s5
	ds_read_b128 v[188:191], v143 offset:16384
	ds_read_b128 v[192:195], v143 offset:17408
	ds_read_b128 v[214:217], v143 offset:18432
	ds_read_b128 v[218:221], v143 offset:19456
	ds_read_b128 v[222:225], v143 offset:20480
	ds_read_b128 v[226:229], v143 offset:21504
	ds_read_b128 v[230:233], v143 offset:22528
	ds_read_b128 v[234:237], v143 offset:23552
	global_load_lds_dwordx4 v[138:139], off
	s_add_i32 m0, s5, 0x2000
	s_add_u32 s36, s64, 0x40000
	v_lshl_add_u64 v[238:239], s[64:65], 0, v[128:129]
	s_addc_u32 s37, s65, 0
	s_add_i32 s4, s4, s23
	global_load_lds_dwordx4 v[238:239], off
	v_lshl_add_u64 v[240:241], s[36:37], 0, v[160:161]
	s_mov_b32 m0, s4
	v_lshl_add_u64 v[242:243], s[66:67], 0, v[130:131]
	global_load_lds_dwordx4 v[240:241], off
	v_lshl_add_u64 v[240:241], s[36:37], 0, v[128:129]
	s_add_i32 m0, s4, 0x2000
	s_nop 0
	global_load_lds_dwordx4 v[240:241], off
	v_lshl_add_u64 v[240:241], s[66:67], 0, v[132:133]
	s_mov_b32 m0, s24
	s_nop 0
	global_load_lds_dwordx4 v[240:241], off
	s_mov_b32 m0, s25
	s_nop 0
	global_load_lds_dwordx4 v[242:243], off
	s_waitcnt vmcnt(8)
	s_waitcnt lgkmcnt(0)
	s_barrier
; #define PG8_STAGE(bufoff, gbase, voff) do { _Pragma("unroll") for (int _i = 0; _i < 2; ++_i) \
;         __builtin_amdgcn_global_load_lds((const unsigned*)((const char*)(gbase) + (voff)[_i]), (LAS unsigned*)(lds + (bufoff) + ldsw + _i * 8192), 16, 0, 0); } while (0)
; #define PG8_LDA(dst, b, h) do { _Pragma("unroll") for (int m = 0; m < 4; ++m) _Pragma("unroll") for (int k = 0; k < 2; ++k) dst[m][k] = *(const LAS bf16x8*)(lds + PG8_SA(b, h) + aoff + m * 2048 + k * 1024); } while (0)
; #define PG8_LDB(dst, b, h) do { _Pragma("unroll") for (int n = 0; n < 2; ++n) _Pragma("unroll") for (int k = 0; k < 2; ++k) dst[n][k] = *(const LAS bf16x8*)(lds + PG8_SB(b, h) + boff + n * 2048 + k * 1024); } while (0)
; #define PG8_WAIT_V(n) asm volatile("s_waitcnt vmcnt(" #n ")" ::: "memory")
; #define PG8_WAIT_L(n) asm volatile("s_waitcnt lgkmcnt(" #n ")" ::: "memory")
; #define PG8_BAR __builtin_amdgcn_s_barrier()
; #define PG8_SCHED __builtin_amdgcn_sched_barrier(0)
; template <class Epi>
; __device__ __forceinline__ void gemm_phase(LAS unsigned char* lds, const Gemm g, const Order& S, const Epi& E) {
;     ...
;             PG8_WAIT_V(8); PG8_WAIT_L(0); PG8_BAR; PG8_MMA(1, 0, At, B0); PG8_MMA(1, 1, At, B1); PG8_BAR; PG8_SCHED;
;             PG8_LDB(B0, 1, 0); PG8_LDB(B1, 1, 1); PG8_SCHED; PG8_LDA(At, 1, 0); PG8_STAGE(PG8_SA(0, 1), a2 + hstepA, voffA);
;             PG8_WAIT_V(8); PG8_WAIT_L(0); PG8_BAR; PG8_MMA(0, 0, At, B0); PG8_MMA(0, 1, At, B1); PG8_BAR; PG8_SCHED;
	s_setprio 1
	v_mfma_f32_16x16x32_f16 v[60:63], v[144:147], v[188:191], v[60:63]
	v_mfma_f32_16x16x32_f16 v[48:51], v[152:155], v[188:191], v[48:51]
	v_mfma_f32_16x16x32_f16 v[44:47], v[144:147], v[214:217], v[44:47]
	v_mfma_f32_16x16x32_f16 v[32:35], v[152:155], v[214:217], v[32:35]
	v_mfma_f32_16x16x32_f16 v[28:31], v[144:147], v[222:225], v[28:31]
	v_mfma_f32_16x16x32_f16 v[16:19], v[152:155], v[222:225], v[16:19]
	v_mfma_f32_16x16x32_f16 v[12:15], v[144:147], v[230:233], v[12:15]
	v_mfma_f32_16x16x32_f16 v[0:3], v[152:155], v[230:233], v[0:3]
	v_mfma_f32_16x16x32_f16 v[60:63], v[148:151], v[192:195], v[60:63]
	v_mfma_f32_16x16x32_f16 v[48:51], v[156:159], v[192:195], v[48:51]
	v_mfma_f32_16x16x32_f16 v[44:47], v[148:151], v[218:221], v[44:47]
	v_mfma_f32_16x16x32_f16 v[32:35], v[156:159], v[218:221], v[32:35]
	v_mfma_f32_16x16x32_f16 v[28:31], v[148:151], v[226:229], v[28:31]
	v_mfma_f32_16x16x32_f16 v[16:19], v[156:159], v[226:229], v[16:19]
	v_mfma_f32_16x16x32_f16 v[12:15], v[148:151], v[234:237], v[12:15]
	v_mfma_f32_16x16x32_f16 v[0:3], v[156:159], v[234:237], v[0:3]
	v_mfma_f32_16x16x32_f16 v[56:59], v[172:175], v[188:191], v[56:59]
	v_mfma_f32_16x16x32_f16 v[52:55], v[180:183], v[188:191], v[52:55]
	v_mfma_f32_16x16x32_f16 v[40:43], v[172:175], v[214:217], v[40:43]
	v_mfma_f32_16x16x32_f16 v[36:39], v[180:183], v[214:217], v[36:39]
	v_mfma_f32_16x16x32_f16 v[24:27], v[172:175], v[222:225], v[24:27]
	v_mfma_f32_16x16x32_f16 v[20:23], v[180:183], v[222:225], v[20:23]
	v_mfma_f32_16x16x32_f16 v[8:11], v[172:175], v[230:233], v[8:11]
	v_mfma_f32_16x16x32_f16 v[4:7], v[180:183], v[230:233], v[4:7]
	v_mfma_f32_16x16x32_f16 v[56:59], v[176:179], v[192:195], v[56:59]
	v_mfma_f32_16x16x32_f16 v[52:55], v[184:187], v[192:195], v[52:55]
	v_mfma_f32_16x16x32_f16 v[40:43], v[176:179], v[218:221], v[40:43]
	v_mfma_f32_16x16x32_f16 v[36:39], v[184:187], v[218:221], v[36:39]
	v_mfma_f32_16x16x32_f16 v[24:27], v[176:179], v[226:229], v[24:27]
	v_mfma_f32_16x16x32_f16 v[20:23], v[184:187], v[226:229], v[20:23]
	v_mfma_f32_16x16x32_f16 v[8:11], v[176:179], v[234:237], v[8:11]
	v_mfma_f32_16x16x32_f16 v[4:7], v[184:187], v[234:237], v[4:7]
	s_setprio 0
	s_barrier
	s_add_i32 s4, 0, 0x18000
	s_add_i32 s5, 0, 0x1c000
	v_add_u32_e32 v156, s4, v141
	v_add_u32_e32 v171, s5, v141
	ds_read_b128 v[144:147], v156
	ds_read_b128 v[148:151], v156 offset:1024
	ds_read_b128 v[152:155], v156 offset:2048
	ds_read_b128 v[156:159], v156 offset:3072
	ds_read_b128 v[172:175], v171
	ds_read_b128 v[176:179], v171 offset:1024
	ds_read_b128 v[180:183], v171 offset:2048
	ds_read_b128 v[184:187], v171 offset:3072
	s_add_u32 s36, s66, 0x40000
	s_addc_u32 s37, s67, 0
	s_mov_b32 m0, s26
	v_lshl_add_u64 v[244:245], s[36:37], 0, v[132:133]
	ds_read_b128 v[188:191], v143 offset:32768
	ds_read_b128 v[192:195], v143 offset:33792
	ds_read_b128 v[214:217], v143 offset:34816
	ds_read_b128 v[218:221], v143 offset:35840
	ds_read_b128 v[222:225], v143 offset:36864
	ds_read_b128 v[226:229], v143 offset:37888
	ds_read_b128 v[230:233], v143 offset:38912
	ds_read_b128 v[234:237], v143 offset:39936
	global_load_lds_dwordx4 v[244:245], off
	v_lshl_add_u64 v[244:245], s[36:37], 0, v[130:131]
	s_mov_b32 m0, s27
	s_nop 0
	global_load_lds_dwordx4 v[244:245], off
	s_waitcnt vmcnt(8)
	s_waitcnt lgkmcnt(0)
	s_barrier
	s_setprio 1
	v_mfma_f32_16x16x32_f16 v[124:127], v[144:147], v[188:191], v[124:127]
	v_mfma_f32_16x16x32_f16 v[112:115], v[152:155], v[188:191], v[112:115]
	v_mfma_f32_16x16x32_f16 v[108:111], v[144:147], v[214:217], v[108:111]
	v_mfma_f32_16x16x32_f16 v[96:99], v[152:155], v[214:217], v[96:99]
	v_mfma_f32_16x16x32_f16 v[92:95], v[144:147], v[222:225], v[92:95]
	v_mfma_f32_16x16x32_f16 v[80:83], v[152:155], v[222:225], v[80:83]
	v_mfma_f32_16x16x32_f16 v[76:79], v[144:147], v[230:233], v[76:79]
	v_mfma_f32_16x16x32_f16 v[64:67], v[152:155], v[230:233], v[64:67]
	v_mfma_f32_16x16x32_f16 v[124:127], v[148:151], v[192:195], v[124:127]
	v_mfma_f32_16x16x32_f16 v[112:115], v[156:159], v[192:195], v[112:115]
	v_mfma_f32_16x16x32_f16 v[108:111], v[148:151], v[218:221], v[108:111]
	v_mfma_f32_16x16x32_f16 v[96:99], v[156:159], v[218:221], v[96:99]
	v_mfma_f32_16x16x32_f16 v[92:95], v[148:151], v[226:229], v[92:95]
	v_mfma_f32_16x16x32_f16 v[80:83], v[156:159], v[226:229], v[80:83]
	v_mfma_f32_16x16x32_f16 v[76:79], v[148:151], v[234:237], v[76:79]
	v_mfma_f32_16x16x32_f16 v[64:67], v[156:159], v[234:237], v[64:67]
	v_mfma_f32_16x16x32_f16 v[120:123], v[172:175], v[188:191], v[120:123]
	v_mfma_f32_16x16x32_f16 v[116:119], v[180:183], v[188:191], v[116:119]
	v_mfma_f32_16x16x32_f16 v[104:107], v[172:175], v[214:217], v[104:107]
	v_mfma_f32_16x16x32_f16 v[100:103], v[180:183], v[214:217], v[100:103]
	v_mfma_f32_16x16x32_f16 v[88:91], v[172:175], v[222:225], v[88:91]
	v_mfma_f32_16x16x32_f16 v[84:87], v[180:183], v[222:225], v[84:87]
	v_mfma_f32_16x16x32_f16 v[72:75], v[172:175], v[230:233], v[72:75]
	v_mfma_f32_16x16x32_f16 v[68:71], v[180:183], v[230:233], v[68:71]
	v_mfma_f32_16x16x32_f16 v[120:123], v[176:179], v[192:195], v[120:123]
	v_mfma_f32_16x16x32_f16 v[116:119], v[184:187], v[192:195], v[116:119]
	v_mfma_f32_16x16x32_f16 v[104:107], v[176:179], v[218:221], v[104:107]
	v_mfma_f32_16x16x32_f16 v[100:103], v[184:187], v[218:221], v[100:103]
	v_mfma_f32_16x16x32_f16 v[88:91], v[176:179], v[226:229], v[88:91]
	v_mfma_f32_16x16x32_f16 v[84:87], v[184:187], v[226:229], v[84:87]
	v_mfma_f32_16x16x32_f16 v[72:75], v[176:179], v[234:237], v[72:75]
	v_mfma_f32_16x16x32_f16 v[68:71], v[184:187], v[234:237], v[68:71]
	s_setprio 0
	s_barrier
; #define PG8_STAGE(bufoff, gbase, voff) do { _Pragma("unroll") for (int _i = 0; _i < 2; ++_i) \
;         __builtin_amdgcn_global_load_lds((const unsigned*)((const char*)(gbase) + (voff)[_i]), (LAS unsigned*)(lds + (bufoff) + ldsw + _i * 8192), 16, 0, 0); } while (0)
; #define PG8_LDA(dst, b, h) do { _Pragma("unroll") for (int m = 0; m < 4; ++m) _Pragma("unroll") for (int k = 0; k < 2; ++k) dst[m][k] = *(const LAS bf16x8*)(lds + PG8_SA(b, h) + aoff + m * 2048 + k * 1024); } while (0)
; #define PG8_WAIT_V(n) asm volatile("s_waitcnt vmcnt(" #n ")" ::: "memory")
; #define PG8_WAIT_L(n) asm volatile("s_waitcnt lgkmcnt(" #n ")" ::: "memory")
; #define PG8_BAR __builtin_amdgcn_s_barrier()
; #define PG8_SCHED __builtin_amdgcn_sched_barrier(0)
; template <class Epi>
; __device__ __forceinline__ void gemm_phase(LAS unsigned char* lds, const Gemm g, const Order& S, const Epi& E) {
;     ...
;             PG8_LDA(At, 1, 1); PG8_STAGE(PG8_SB(1, 0), b3, voffB); PG8_STAGE(PG8_SB(1, 1), b3 + hstepB, voffB); PG8_STAGE(PG8_SA(1, 0), a3, voffA);
;             PG8_WAIT_V(8); PG8_WAIT_L(0); PG8_BAR; PG8_MMA(1, 0, At, B0); PG8_MMA(1, 1, At, B1); PG8_BAR; PG8_SCHED;
;         }
;         if constexpr (ALIGN_EPI) { if (wr == 0) PG8_BAR; }
;         if constexpr (!Epi::AFTER_DRAIN) E(acc, cur, wr, wc, fr, fq);
;         if (!has_next) break;
	s_add_i32 s4, s4, s23
	v_lshl_add_u64 v[138:139], v[138:139], 0, s[62:63]
	s_mov_b32 m0, s4
	ds_read_b128 v[188:191], v143 offset:49152
	ds_read_b128 v[192:195], v143 offset:50176
	ds_read_b128 v[214:217], v143 offset:51200
	ds_read_b128 v[218:221], v143 offset:52224
	ds_read_b128 v[222:225], v143 offset:53248
	ds_read_b128 v[226:229], v143 offset:54272
	ds_read_b128 v[230:233], v143 offset:55296
	ds_read_b128 v[234:237], v143 offset:56320
	global_load_lds_dwordx4 v[138:139], off
	s_add_i32 m0, s4, 0x2000
	s_add_u32 s36, s64, 0x40080
	v_lshl_add_u64 v[138:139], v[238:239], 0, s[62:63]
	s_addc_u32 s37, s65, 0
	s_add_i32 s4, s5, s23
	global_load_lds_dwordx4 v[138:139], off
	v_lshl_add_u64 v[138:139], s[36:37], 0, v[160:161]
	s_mov_b32 m0, s4
	s_nop 0
	global_load_lds_dwordx4 v[138:139], off
	v_lshl_add_u64 v[138:139], s[36:37], 0, v[128:129]
	s_add_i32 m0, s4, 0x2000
	s_nop 0
	global_load_lds_dwordx4 v[138:139], off
	v_lshl_add_u64 v[138:139], v[240:241], 0, s[62:63]
	s_mov_b32 m0, s28
	s_nop 0
	global_load_lds_dwordx4 v[138:139], off
	v_lshl_add_u64 v[138:139], v[242:243], 0, s[62:63]
	s_mov_b32 m0, s29
	s_nop 0
	global_load_lds_dwordx4 v[138:139], off
	s_waitcnt vmcnt(8)
	s_waitcnt lgkmcnt(0)
	s_barrier
	s_setprio 1
	v_mfma_f32_16x16x32_f16 v[60:63], v[144:147], v[188:191], v[60:63]
	v_mfma_f32_16x16x32_f16 v[48:51], v[152:155], v[188:191], v[48:51]
	v_mfma_f32_16x16x32_f16 v[44:47], v[144:147], v[214:217], v[44:47]
	v_mfma_f32_16x16x32_f16 v[32:35], v[152:155], v[214:217], v[32:35]
	v_mfma_f32_16x16x32_f16 v[28:31], v[144:147], v[222:225], v[28:31]
	v_mfma_f32_16x16x32_f16 v[16:19], v[152:155], v[222:225], v[16:19]
	v_mfma_f32_16x16x32_f16 v[12:15], v[144:147], v[230:233], v[12:15]
	v_mfma_f32_16x16x32_f16 v[0:3], v[152:155], v[230:233], v[0:3]
	v_mfma_f32_16x16x32_f16 v[60:63], v[148:151], v[192:195], v[60:63]
	v_mfma_f32_16x16x32_f16 v[48:51], v[156:159], v[192:195], v[48:51]
	v_mfma_f32_16x16x32_f16 v[44:47], v[148:151], v[218:221], v[44:47]
	v_mfma_f32_16x16x32_f16 v[32:35], v[156:159], v[218:221], v[32:35]
	v_mfma_f32_16x16x32_f16 v[28:31], v[148:151], v[226:229], v[28:31]
	v_mfma_f32_16x16x32_f16 v[16:19], v[156:159], v[226:229], v[16:19]
	v_mfma_f32_16x16x32_f16 v[12:15], v[148:151], v[234:237], v[12:15]
	v_mfma_f32_16x16x32_f16 v[0:3], v[156:159], v[234:237], v[0:3]
	v_mfma_f32_16x16x32_f16 v[56:59], v[172:175], v[188:191], v[56:59]
	v_mfma_f32_16x16x32_f16 v[52:55], v[180:183], v[188:191], v[52:55]
	v_mfma_f32_16x16x32_f16 v[40:43], v[172:175], v[214:217], v[40:43]
	v_mfma_f32_16x16x32_f16 v[36:39], v[180:183], v[214:217], v[36:39]
	v_mfma_f32_16x16x32_f16 v[24:27], v[172:175], v[222:225], v[24:27]
	v_mfma_f32_16x16x32_f16 v[20:23], v[180:183], v[222:225], v[20:23]
	v_mfma_f32_16x16x32_f16 v[8:11], v[172:175], v[230:233], v[8:11]
	v_mfma_f32_16x16x32_f16 v[4:7], v[180:183], v[230:233], v[4:7]
	v_mfma_f32_16x16x32_f16 v[56:59], v[176:179], v[192:195], v[56:59]
	v_mfma_f32_16x16x32_f16 v[52:55], v[184:187], v[192:195], v[52:55]
	v_mfma_f32_16x16x32_f16 v[40:43], v[176:179], v[218:221], v[40:43]
	v_mfma_f32_16x16x32_f16 v[36:39], v[184:187], v[218:221], v[36:39]
	v_mfma_f32_16x16x32_f16 v[24:27], v[176:179], v[226:229], v[24:27]
	v_mfma_f32_16x16x32_f16 v[20:23], v[184:187], v[226:229], v[20:23]
	v_mfma_f32_16x16x32_f16 v[8:11], v[176:179], v[234:237], v[8:11]
	v_mfma_f32_16x16x32_f16 v[4:7], v[184:187], v[234:237], v[4:7]
	s_setprio 0
	s_barrier
	s_add_i32 s71, s71, 2
	s_add_u32 s50, s50, 0x100
	s_addc_u32 s51, s51, 0
	s_add_u32 s69, s69, 0x100
	s_addc_u32 s70, s70, 0
	s_cmp_gt_u32 s71, 13
	s_cbranch_scc0 .LBB0_396
	s_and_b64 vcc, exec, s[40:41]
	s_cbranch_vccz .LBB0_399
	s_barrier

; #define PG8_STAGE(bufoff, gbase, voff) do { _Pragma("unroll") for (int _i = 0; _i < 2; ++_i) \
;         __builtin_amdgcn_global_load_lds((const unsigned*)((const char*)(gbase) + (voff)[_i]), (LAS unsigned*)(lds + (bufoff) + ldsw + _i * 8192), 16, 0, 0); } while (0)
; #define PG8_LDA(dst, b, h) do { _Pragma("unroll") for (int m = 0; m < 4; ++m) _Pragma("unroll") for (int k = 0; k < 2; ++k) dst[m][k] = *(const LAS bf16x8*)(lds + PG8_SA(b, h) + aoff + m * 2048 + k * 1024); } while (0)
; #define PG8_LDB(dst, b, h) do { _Pragma("unroll") for (int n = 0; n < 2; ++n) _Pragma("unroll") for (int k = 0; k < 2; ++k) dst[n][k] = *(const LAS bf16x8*)(lds + PG8_SB(b, h) + boff + n * 2048 + k * 1024); } while (0)
; #define PG8_WAIT_V(n) asm volatile("s_waitcnt vmcnt(" #n ")" ::: "memory")
; #define PG8_WAIT_L(n) asm volatile("s_waitcnt lgkmcnt(" #n ")" ::: "memory")
; #define PG8_BAR __builtin_amdgcn_s_barrier()
; #define PG8_SCHED __builtin_amdgcn_sched_barrier(0)
; template <class Epi>
; __device__ __forceinline__ void gemm_phase(LAS unsigned char* lds, const Gemm g, const Order& S, const Epi& E) {
;     ...
;             const bool last = (t == nt - 2);
;             const char* a1 = cA + (size_t)(t + 1) * kstep;
;             const char* a2 = last ? nA : cA + (size_t)(t + 2) * kstep; const char* b2 = last ? nB : cB + (size_t)(t + 2) * kstep;
;             const char* a3 = a2 + kstep; const char* b3 = b2 + kstep;
;             PG8_LDB(B0, 0, 0); PG8_LDB(B1, 0, 1); PG8_SCHED; PG8_LDA(At, 0, 0); PG8_STAGE(PG8_SA(1, 1), a1 + hstepA, voffA);
;             PG8_WAIT_V(8); PG8_WAIT_L(0); PG8_BAR; PG8_MMA(0, 0, At, B0); PG8_MMA(0, 1, At, B1); PG8_BAR; PG8_SCHED;
;             PG8_LDA(At, 0, 1); PG8_STAGE(PG8_SB(0, 0), b2, voffB); PG8_STAGE(PG8_SB(0, 1), b2 + hstepB, voffB); PG8_STAGE(PG8_SA(0, 0), a2, voffA);
;             PG8_WAIT_V(8); PG8_WAIT_L(0); PG8_BAR; PG8_MMA(1, 0, At, B0); PG8_MMA(1, 1, At, B1); PG8_BAR; PG8_SCHED;
.LBB0_413:
	s_add_u32 s4, s48, 0xfffc0080
	s_addc_u32 s5, s49, -1
	s_add_i32 s36, 0, 0x10000
	s_cmp_eq_u32 s66, 12
	s_cselect_b32 s65, s30, s5
	s_cselect_b32 s64, s31, s4
	v_add_u32_e32 v138, s36, v141
	s_cselect_b32 s51, s34, s43
	s_cselect_b32 s50, s35, s41
	s_add_i32 s4, 0, 0x14000
	ds_read_b128 v[144:147], v138
	ds_read_b128 v[148:151], v138 offset:1024
	ds_read_b128 v[152:155], v138 offset:2048
	ds_read_b128 v[156:159], v138 offset:3072
	v_add_u32_e32 v138, s4, v141
	ds_read_b128 v[172:175], v138
	ds_read_b128 v[176:179], v138 offset:1024
	ds_read_b128 v[180:183], v138 offset:2048
	ds_read_b128 v[184:187], v138 offset:3072
	v_lshl_add_u64 v[138:139], s[48:49], 0, v[134:135]
	s_add_i32 m0, s21, 0xc000
	ds_read_b128 v[188:191], v143
	ds_read_b128 v[192:195], v143 offset:1024
	ds_read_b128 v[214:217], v143 offset:2048
	ds_read_b128 v[218:221], v143 offset:3072
	ds_read_b128 v[222:225], v143 offset:4096
	ds_read_b128 v[226:229], v143 offset:5120
	ds_read_b128 v[230:233], v143 offset:6144
	ds_read_b128 v[234:237], v143 offset:7168
	global_load_lds_dwordx4 v[138:139], off
	v_lshl_add_u64 v[138:139], s[48:49], 0, v[136:137]
	s_add_i32 m0, s21, 0xe000
	s_nop 0
	global_load_lds_dwordx4 v[138:139], off
	s_waitcnt vmcnt(8)
	s_waitcnt lgkmcnt(0)
	s_barrier
	s_setprio 1
	v_mfma_f32_16x16x32_bf16 v[124:127], v[144:147], v[188:191], v[124:127]
	v_mfma_f32_16x16x32_bf16 v[120:123], v[152:155], v[188:191], v[120:123]
	v_mfma_f32_16x16x32_bf16 v[116:119], v[144:147], v[214:217], v[116:119]
	v_mfma_f32_16x16x32_bf16 v[108:111], v[152:155], v[214:217], v[108:111]
	v_mfma_f32_16x16x32_bf16 v[100:103], v[144:147], v[222:225], v[100:103]
	v_mfma_f32_16x16x32_bf16 v[92:95], v[152:155], v[222:225], v[92:95]
	v_mfma_f32_16x16x32_bf16 v[84:87], v[144:147], v[230:233], v[84:87]
	v_mfma_f32_16x16x32_bf16 v[76:79], v[152:155], v[230:233], v[76:79]
	v_mfma_f32_16x16x32_bf16 v[124:127], v[148:151], v[192:195], v[124:127]
	v_mfma_f32_16x16x32_bf16 v[120:123], v[156:159], v[192:195], v[120:123]
	v_mfma_f32_16x16x32_bf16 v[116:119], v[148:151], v[218:221], v[116:119]
	v_mfma_f32_16x16x32_bf16 v[108:111], v[156:159], v[218:221], v[108:111]
	v_mfma_f32_16x16x32_bf16 v[100:103], v[148:151], v[226:229], v[100:103]
	v_mfma_f32_16x16x32_bf16 v[92:95], v[156:159], v[226:229], v[92:95]
	v_mfma_f32_16x16x32_bf16 v[84:87], v[148:151], v[234:237], v[84:87]
	v_mfma_f32_16x16x32_bf16 v[76:79], v[156:159], v[234:237], v[76:79]
	v_mfma_f32_16x16x32_bf16 v[112:115], v[172:175], v[188:191], v[112:115]
	v_mfma_f32_16x16x32_bf16 v[104:107], v[180:183], v[188:191], v[104:107]
	v_mfma_f32_16x16x32_bf16 v[96:99], v[172:175], v[214:217], v[96:99]
	v_mfma_f32_16x16x32_bf16 v[88:91], v[180:183], v[214:217], v[88:91]
	v_mfma_f32_16x16x32_bf16 v[80:83], v[172:175], v[222:225], v[80:83]
	v_mfma_f32_16x16x32_bf16 v[72:75], v[180:183], v[222:225], v[72:75]
	v_mfma_f32_16x16x32_bf16 v[68:71], v[172:175], v[230:233], v[68:71]
	v_mfma_f32_16x16x32_bf16 v[64:67], v[180:183], v[230:233], v[64:67]
	v_mfma_f32_16x16x32_bf16 v[112:115], v[176:179], v[192:195], v[112:115]
	v_mfma_f32_16x16x32_bf16 v[104:107], v[184:187], v[192:195], v[104:107]
	v_mfma_f32_16x16x32_bf16 v[96:99], v[176:179], v[218:221], v[96:99]
	v_mfma_f32_16x16x32_bf16 v[88:91], v[184:187], v[218:221], v[88:91]
	v_mfma_f32_16x16x32_bf16 v[80:83], v[176:179], v[226:229], v[80:83]
	v_mfma_f32_16x16x32_bf16 v[72:75], v[184:187], v[226:229], v[72:75]
	v_mfma_f32_16x16x32_bf16 v[68:71], v[176:179], v[234:237], v[68:71]
	v_mfma_f32_16x16x32_bf16 v[64:67], v[184:187], v[234:237], v[64:67]
	s_setprio 0
	s_barrier
	s_add_i32 s5, s36, s1
	v_lshl_add_u64 v[138:139], s[50:51], 0, v[160:161]
	s_mov_b32 m0, s5
	ds_read_b128 v[188:191], v143 offset:16384
	ds_read_b128 v[192:195], v143 offset:17408
	ds_read_b128 v[214:217], v143 offset:18432
	ds_read_b128 v[218:221], v143 offset:19456
	ds_read_b128 v[222:225], v143 offset:20480
	ds_read_b128 v[226:229], v143 offset:21504
	ds_read_b128 v[230:233], v143 offset:22528
	ds_read_b128 v[234:237], v143 offset:23552
	global_load_lds_dwordx4 v[138:139], off
	s_add_i32 m0, s5, 0x2000
	s_add_u32 s36, s50, 0x40000
	v_lshl_add_u64 v[238:239], s[50:51], 0, v[128:129]
	s_addc_u32 s37, s51, 0
	s_add_i32 s4, s4, s1
	global_load_lds_dwordx4 v[238:239], off
	v_lshl_add_u64 v[240:241], s[36:37], 0, v[160:161]
	s_mov_b32 m0, s4
	v_lshl_add_u64 v[242:243], s[64:65], 0, v[130:131]
	global_load_lds_dwordx4 v[240:241], off
	v_lshl_add_u64 v[240:241], s[36:37], 0, v[128:129]
	s_add_i32 m0, s4, 0x2000
	s_nop 0
	global_load_lds_dwordx4 v[240:241], off
	v_lshl_add_u64 v[240:241], s[64:65], 0, v[132:133]
	s_mov_b32 m0, s21
	s_nop 0
	global_load_lds_dwordx4 v[240:241], off
	s_mov_b32 m0, s22
	s_nop 0
	global_load_lds_dwordx4 v[242:243], off
	s_waitcnt vmcnt(8)
	s_waitcnt lgkmcnt(0)
	s_barrier
; #define PG8_STAGE(bufoff, gbase, voff) do { _Pragma("unroll") for (int _i = 0; _i < 2; ++_i) \
;         __builtin_amdgcn_global_load_lds((const unsigned*)((const char*)(gbase) + (voff)[_i]), (LAS unsigned*)(lds + (bufoff) + ldsw + _i * 8192), 16, 0, 0); } while (0)
; #define PG8_LDA(dst, b, h) do { _Pragma("unroll") for (int m = 0; m < 4; ++m) _Pragma("unroll") for (int k = 0; k < 2; ++k) dst[m][k] = *(const LAS bf16x8*)(lds + PG8_SA(b, h) + aoff + m * 2048 + k * 1024); } while (0)
; #define PG8_LDB(dst, b, h) do { _Pragma("unroll") for (int n = 0; n < 2; ++n) _Pragma("unroll") for (int k = 0; k < 2; ++k) dst[n][k] = *(const LAS bf16x8*)(lds + PG8_SB(b, h) + boff + n * 2048 + k * 1024); } while (0)
; #define PG8_WAIT_V(n) asm volatile("s_waitcnt vmcnt(" #n ")" ::: "memory")
; #define PG8_WAIT_L(n) asm volatile("s_waitcnt lgkmcnt(" #n ")" ::: "memory")
; #define PG8_BAR __builtin_amdgcn_s_barrier()
; #define PG8_SCHED __builtin_amdgcn_sched_barrier(0)
; template <class Epi>
; __device__ __forceinline__ void gemm_phase(LAS unsigned char* lds, const Gemm g, const Order& S, const Epi& E) {
;     ...
;             PG8_WAIT_V(8); PG8_WAIT_L(0); PG8_BAR; PG8_MMA(1, 0, At, B0); PG8_MMA(1, 1, At, B1); PG8_BAR; PG8_SCHED;
;             PG8_LDB(B0, 1, 0); PG8_LDB(B1, 1, 1); PG8_SCHED; PG8_LDA(At, 1, 0); PG8_STAGE(PG8_SA(0, 1), a2 + hstepA, voffA);
;             PG8_WAIT_V(8); PG8_WAIT_L(0); PG8_BAR; PG8_MMA(0, 0, At, B0); PG8_MMA(0, 1, At, B1); PG8_BAR; PG8_SCHED;
	s_setprio 1
	v_mfma_f32_16x16x32_bf16 v[60:63], v[144:147], v[188:191], v[60:63]
	v_mfma_f32_16x16x32_bf16 v[56:59], v[152:155], v[188:191], v[56:59]
	v_mfma_f32_16x16x32_bf16 v[52:55], v[144:147], v[214:217], v[52:55]
	v_mfma_f32_16x16x32_bf16 v[44:47], v[152:155], v[214:217], v[44:47]
	v_mfma_f32_16x16x32_bf16 v[36:39], v[144:147], v[222:225], v[36:39]
	v_mfma_f32_16x16x32_bf16 v[28:31], v[152:155], v[222:225], v[28:31]
	v_mfma_f32_16x16x32_bf16 v[20:23], v[144:147], v[230:233], v[20:23]
	v_mfma_f32_16x16x32_bf16 v[12:15], v[152:155], v[230:233], v[12:15]
	v_mfma_f32_16x16x32_bf16 v[60:63], v[148:151], v[192:195], v[60:63]
	v_mfma_f32_16x16x32_bf16 v[56:59], v[156:159], v[192:195], v[56:59]
	v_mfma_f32_16x16x32_bf16 v[52:55], v[148:151], v[218:221], v[52:55]
	v_mfma_f32_16x16x32_bf16 v[44:47], v[156:159], v[218:221], v[44:47]
	v_mfma_f32_16x16x32_bf16 v[36:39], v[148:151], v[226:229], v[36:39]
	v_mfma_f32_16x16x32_bf16 v[28:31], v[156:159], v[226:229], v[28:31]
	v_mfma_f32_16x16x32_bf16 v[20:23], v[148:151], v[234:237], v[20:23]
	v_mfma_f32_16x16x32_bf16 v[12:15], v[156:159], v[234:237], v[12:15]
	v_mfma_f32_16x16x32_bf16 v[48:51], v[172:175], v[188:191], v[48:51]
	v_mfma_f32_16x16x32_bf16 v[40:43], v[180:183], v[188:191], v[40:43]
	v_mfma_f32_16x16x32_bf16 v[32:35], v[172:175], v[214:217], v[32:35]
	v_mfma_f32_16x16x32_bf16 v[24:27], v[180:183], v[214:217], v[24:27]
	v_mfma_f32_16x16x32_bf16 v[16:19], v[172:175], v[222:225], v[16:19]
	v_mfma_f32_16x16x32_bf16 v[8:11], v[180:183], v[222:225], v[8:11]
	v_mfma_f32_16x16x32_bf16 v[4:7], v[172:175], v[230:233], v[4:7]
	v_mfma_f32_16x16x32_bf16 v[0:3], v[180:183], v[230:233], v[0:3]
	v_mfma_f32_16x16x32_bf16 v[48:51], v[176:179], v[192:195], v[48:51]
	v_mfma_f32_16x16x32_bf16 v[40:43], v[184:187], v[192:195], v[40:43]
	v_mfma_f32_16x16x32_bf16 v[32:35], v[176:179], v[218:221], v[32:35]
	v_mfma_f32_16x16x32_bf16 v[24:27], v[184:187], v[218:221], v[24:27]
	v_mfma_f32_16x16x32_bf16 v[16:19], v[176:179], v[226:229], v[16:19]
	v_mfma_f32_16x16x32_bf16 v[8:11], v[184:187], v[226:229], v[8:11]
	v_mfma_f32_16x16x32_bf16 v[4:7], v[176:179], v[234:237], v[4:7]
	v_mfma_f32_16x16x32_bf16 v[0:3], v[184:187], v[234:237], v[0:3]
	s_setprio 0
	s_barrier
	s_add_i32 s4, 0, 0x18000
	s_add_i32 s5, 0, 0x1c000
	v_add_u32_e32 v156, s4, v141
	v_add_u32_e32 v171, s5, v141
	ds_read_b128 v[144:147], v156
	ds_read_b128 v[148:151], v156 offset:1024
	ds_read_b128 v[152:155], v156 offset:2048
	ds_read_b128 v[156:159], v156 offset:3072
	ds_read_b128 v[172:175], v171
	ds_read_b128 v[176:179], v171 offset:1024
	ds_read_b128 v[180:183], v171 offset:2048
	ds_read_b128 v[184:187], v171 offset:3072
	s_add_u32 s36, s64, 0x40000
	s_addc_u32 s37, s65, 0
	s_mov_b32 m0, s23
	v_lshl_add_u64 v[244:245], s[36:37], 0, v[132:133]
	ds_read_b128 v[188:191], v143 offset:32768
	ds_read_b128 v[192:195], v143 offset:33792
	ds_read_b128 v[214:217], v143 offset:34816
	ds_read_b128 v[218:221], v143 offset:35840
	ds_read_b128 v[222:225], v143 offset:36864
	ds_read_b128 v[226:229], v143 offset:37888
	ds_read_b128 v[230:233], v143 offset:38912
	ds_read_b128 v[234:237], v143 offset:39936
	global_load_lds_dwordx4 v[244:245], off
	v_lshl_add_u64 v[244:245], s[36:37], 0, v[130:131]
	s_mov_b32 m0, s24
	s_nop 0
	global_load_lds_dwordx4 v[244:245], off
	s_waitcnt vmcnt(8)
	s_waitcnt lgkmcnt(0)
	s_barrier
	s_setprio 1
	v_mfma_f32_16x16x32_bf16 v[124:127], v[144:147], v[188:191], v[124:127]
	v_mfma_f32_16x16x32_bf16 v[120:123], v[152:155], v[188:191], v[120:123]
	v_mfma_f32_16x16x32_bf16 v[116:119], v[144:147], v[214:217], v[116:119]
	v_mfma_f32_16x16x32_bf16 v[108:111], v[152:155], v[214:217], v[108:111]
	v_mfma_f32_16x16x32_bf16 v[100:103], v[144:147], v[222:225], v[100:103]
	v_mfma_f32_16x16x32_bf16 v[92:95], v[152:155], v[222:225], v[92:95]
	v_mfma_f32_16x16x32_bf16 v[84:87], v[144:147], v[230:233], v[84:87]
	v_mfma_f32_16x16x32_bf16 v[76:79], v[152:155], v[230:233], v[76:79]
	v_mfma_f32_16x16x32_bf16 v[124:127], v[148:151], v[192:195], v[124:127]
	v_mfma_f32_16x16x32_bf16 v[120:123], v[156:159], v[192:195], v[120:123]
	v_mfma_f32_16x16x32_bf16 v[116:119], v[148:151], v[218:221], v[116:119]
	v_mfma_f32_16x16x32_bf16 v[108:111], v[156:159], v[218:221], v[108:111]
	v_mfma_f32_16x16x32_bf16 v[100:103], v[148:151], v[226:229], v[100:103]
	v_mfma_f32_16x16x32_bf16 v[92:95], v[156:159], v[226:229], v[92:95]
	v_mfma_f32_16x16x32_bf16 v[84:87], v[148:151], v[234:237], v[84:87]
	v_mfma_f32_16x16x32_bf16 v[76:79], v[156:159], v[234:237], v[76:79]
	v_mfma_f32_16x16x32_bf16 v[112:115], v[172:175], v[188:191], v[112:115]
	v_mfma_f32_16x16x32_bf16 v[104:107], v[180:183], v[188:191], v[104:107]
	v_mfma_f32_16x16x32_bf16 v[96:99], v[172:175], v[214:217], v[96:99]
	v_mfma_f32_16x16x32_bf16 v[88:91], v[180:183], v[214:217], v[88:91]
	v_mfma_f32_16x16x32_bf16 v[80:83], v[172:175], v[222:225], v[80:83]
	v_mfma_f32_16x16x32_bf16 v[72:75], v[180:183], v[222:225], v[72:75]
	v_mfma_f32_16x16x32_bf16 v[68:71], v[172:175], v[230:233], v[68:71]
	v_mfma_f32_16x16x32_bf16 v[64:67], v[180:183], v[230:233], v[64:67]
	v_mfma_f32_16x16x32_bf16 v[112:115], v[176:179], v[192:195], v[112:115]
	v_mfma_f32_16x16x32_bf16 v[104:107], v[184:187], v[192:195], v[104:107]
	v_mfma_f32_16x16x32_bf16 v[96:99], v[176:179], v[218:221], v[96:99]
	v_mfma_f32_16x16x32_bf16 v[88:91], v[184:187], v[218:221], v[88:91]
	v_mfma_f32_16x16x32_bf16 v[80:83], v[176:179], v[226:229], v[80:83]
	v_mfma_f32_16x16x32_bf16 v[72:75], v[184:187], v[226:229], v[72:75]
	v_mfma_f32_16x16x32_bf16 v[68:71], v[176:179], v[234:237], v[68:71]
	v_mfma_f32_16x16x32_bf16 v[64:67], v[184:187], v[234:237], v[64:67]
	s_setprio 0
	s_barrier
; #define PG8_STAGE(bufoff, gbase, voff) do { _Pragma("unroll") for (int _i = 0; _i < 2; ++_i) \
;         __builtin_amdgcn_global_load_lds((const unsigned*)((const char*)(gbase) + (voff)[_i]), (LAS unsigned*)(lds + (bufoff) + ldsw + _i * 8192), 16, 0, 0); } while (0)
; #define PG8_LDA(dst, b, h) do { _Pragma("unroll") for (int m = 0; m < 4; ++m) _Pragma("unroll") for (int k = 0; k < 2; ++k) dst[m][k] = *(const LAS bf16x8*)(lds + PG8_SA(b, h) + aoff + m * 2048 + k * 1024); } while (0)
; #define PG8_WAIT_V(n) asm volatile("s_waitcnt vmcnt(" #n ")" ::: "memory")
; #define PG8_WAIT_L(n) asm volatile("s_waitcnt lgkmcnt(" #n ")" ::: "memory")
; #define PG8_BAR __builtin_amdgcn_s_barrier()
; #define PG8_SCHED __builtin_amdgcn_sched_barrier(0)
; template <class Epi>
; __device__ __forceinline__ void gemm_phase(LAS unsigned char* lds, const Gemm g, const Order& S, const Epi& E) {
;     ...
;             PG8_LDA(At, 1, 1); PG8_STAGE(PG8_SB(1, 0), b3, voffB); PG8_STAGE(PG8_SB(1, 1), b3 + hstepB, voffB); PG8_STAGE(PG8_SA(1, 0), a3, voffA);
;             PG8_WAIT_V(8); PG8_WAIT_L(0); PG8_BAR; PG8_MMA(1, 0, At, B0); PG8_MMA(1, 1, At, B1); PG8_BAR; PG8_SCHED;
;         }
;         if constexpr (ALIGN_EPI) { if (wr == 0) PG8_BAR; }
;         if constexpr (!Epi::AFTER_DRAIN) E(acc, cur, wr, wc, fr, fq);
;         if (!has_next) break;
	s_add_i32 s4, s4, s1
	v_lshl_add_u64 v[138:139], v[138:139], 0, s[62:63]
	s_mov_b32 m0, s4
	ds_read_b128 v[188:191], v143 offset:49152
	ds_read_b128 v[192:195], v143 offset:50176
	ds_read_b128 v[214:217], v143 offset:51200
	ds_read_b128 v[218:221], v143 offset:52224
	ds_read_b128 v[222:225], v143 offset:53248
	ds_read_b128 v[226:229], v143 offset:54272
	ds_read_b128 v[230:233], v143 offset:55296
	ds_read_b128 v[234:237], v143 offset:56320
	global_load_lds_dwordx4 v[138:139], off
	s_add_i32 m0, s4, 0x2000
	s_add_u32 s36, s50, 0x40080
	v_lshl_add_u64 v[138:139], v[238:239], 0, s[62:63]
	s_addc_u32 s37, s51, 0
	s_add_i32 s4, s5, s1
	global_load_lds_dwordx4 v[138:139], off
	v_lshl_add_u64 v[138:139], s[36:37], 0, v[160:161]
	s_mov_b32 m0, s4
	s_nop 0
	global_load_lds_dwordx4 v[138:139], off
	v_lshl_add_u64 v[138:139], s[36:37], 0, v[128:129]
	s_add_i32 m0, s4, 0x2000
	s_nop 0
	global_load_lds_dwordx4 v[138:139], off
	v_lshl_add_u64 v[138:139], v[240:241], 0, s[62:63]
	s_mov_b32 m0, s25
	s_nop 0
	global_load_lds_dwordx4 v[138:139], off
	v_lshl_add_u64 v[138:139], v[242:243], 0, s[62:63]
	s_mov_b32 m0, s26
	s_nop 0
	global_load_lds_dwordx4 v[138:139], off
	s_waitcnt vmcnt(8)
	s_waitcnt lgkmcnt(0)
	s_barrier
	s_setprio 1
	v_mfma_f32_16x16x32_bf16 v[60:63], v[144:147], v[188:191], v[60:63]
	v_mfma_f32_16x16x32_bf16 v[56:59], v[152:155], v[188:191], v[56:59]
	v_mfma_f32_16x16x32_bf16 v[52:55], v[144:147], v[214:217], v[52:55]
	v_mfma_f32_16x16x32_bf16 v[44:47], v[152:155], v[214:217], v[44:47]
	v_mfma_f32_16x16x32_bf16 v[36:39], v[144:147], v[222:225], v[36:39]
	v_mfma_f32_16x16x32_bf16 v[28:31], v[152:155], v[222:225], v[28:31]
	v_mfma_f32_16x16x32_bf16 v[20:23], v[144:147], v[230:233], v[20:23]
	v_mfma_f32_16x16x32_bf16 v[12:15], v[152:155], v[230:233], v[12:15]
	v_mfma_f32_16x16x32_bf16 v[60:63], v[148:151], v[192:195], v[60:63]
	v_mfma_f32_16x16x32_bf16 v[56:59], v[156:159], v[192:195], v[56:59]
	v_mfma_f32_16x16x32_bf16 v[52:55], v[148:151], v[218:221], v[52:55]
	v_mfma_f32_16x16x32_bf16 v[44:47], v[156:159], v[218:221], v[44:47]
	v_mfma_f32_16x16x32_bf16 v[36:39], v[148:151], v[226:229], v[36:39]
	v_mfma_f32_16x16x32_bf16 v[28:31], v[156:159], v[226:229], v[28:31]
	v_mfma_f32_16x16x32_bf16 v[20:23], v[148:151], v[234:237], v[20:23]
	v_mfma_f32_16x16x32_bf16 v[12:15], v[156:159], v[234:237], v[12:15]
	v_mfma_f32_16x16x32_bf16 v[48:51], v[172:175], v[188:191], v[48:51]
	v_mfma_f32_16x16x32_bf16 v[40:43], v[180:183], v[188:191], v[40:43]
	v_mfma_f32_16x16x32_bf16 v[32:35], v[172:175], v[214:217], v[32:35]
	v_mfma_f32_16x16x32_bf16 v[24:27], v[180:183], v[214:217], v[24:27]
	v_mfma_f32_16x16x32_bf16 v[16:19], v[172:175], v[222:225], v[16:19]
	v_mfma_f32_16x16x32_bf16 v[8:11], v[180:183], v[222:225], v[8:11]
	v_mfma_f32_16x16x32_bf16 v[4:7], v[172:175], v[230:233], v[4:7]
	v_mfma_f32_16x16x32_bf16 v[0:3], v[180:183], v[230:233], v[0:3]
	v_mfma_f32_16x16x32_bf16 v[48:51], v[176:179], v[192:195], v[48:51]
	v_mfma_f32_16x16x32_bf16 v[40:43], v[184:187], v[192:195], v[40:43]
	v_mfma_f32_16x16x32_bf16 v[32:35], v[176:179], v[218:221], v[32:35]
	v_mfma_f32_16x16x32_bf16 v[24:27], v[184:187], v[218:221], v[24:27]
	v_mfma_f32_16x16x32_bf16 v[16:19], v[176:179], v[226:229], v[16:19]
	v_mfma_f32_16x16x32_bf16 v[8:11], v[184:187], v[226:229], v[8:11]
	v_mfma_f32_16x16x32_bf16 v[4:7], v[176:179], v[234:237], v[4:7]
	v_mfma_f32_16x16x32_bf16 v[0:3], v[184:187], v[234:237], v[0:3]
	s_setprio 0
	s_barrier
	s_add_i32 s66, s66, 2
	s_add_u32 s48, s48, 0x100
	s_addc_u32 s49, s49, 0
	s_add_u32 s41, s41, 0x100
	s_addc_u32 s43, s43, 0
	s_cmp_gt_u32 s66, 13
	s_cbranch_scc0 .LBB0_413
	s_and_b64 vcc, exec, s[12:13]
	s_cbranch_vccz .LBB0_416
	s_barrier
